# v19 + FFN-up/w_in: tile ssq block (16 KB) staged by LDS-DMA into 16 KB extra static LDS during the K loop, epilogue head reads it with ds_read_b128 instead of 8 global loads
# speedup vs baseline: 1.0046x; 1.0037x over previous
; #define PG8_STAGE(bufoff, gbase, voff) do { _Pragma("unroll") for (int _i = 0; _i < 2; ++_i) \
;         __builtin_amdgcn_global_load_lds((const unsigned*)((const char*)(gbase) + (voff)[_i]), (LAS unsigned*)(lds + (bufoff) + ldsw + _i * 8192), 16, 0, 0); } while (0)
; #define PG8_LDA(dst, b, h) do { _Pragma("unroll") for (int m = 0; m < 4; ++m) _Pragma("unroll") for (int k = 0; k < 2; ++k) dst[m][k] = *(const LAS bf16x8*)(lds + PG8_SA(b, h) + aoff + m * 2048 + k * 1024); } while (0)
; #define PG8_LDB(dst, b, h) do { _Pragma("unroll") for (int n = 0; n < 2; ++n) _Pragma("unroll") for (int k = 0; k < 2; ++k) dst[n][k] = *(const LAS bf16x8*)(lds + PG8_SB(b, h) + boff + n * 2048 + k * 1024); } while (0)
; #define PG8_MMA(ai, bj, At, Bt) do { __builtin_amdgcn_s_setprio(1); _Pragma("unroll") for (int m = 0; m < 4; ++m) _Pragma("unroll") for (int n = 0; n < 2; ++n) _Pragma("unroll") for (int k = 0; k < 2; ++k) \
;         acc[ai][bj][m][n] = __builtin_amdgcn_mfma_f32_16x16x32_bf16(Bt[n][k], At[m][k], acc[ai][bj][m][n], 0, 0, 0); __builtin_amdgcn_s_setprio(0); } while (0)
; #define PG8_WAIT_V(n) asm volatile("s_waitcnt vmcnt(" #n ")" ::: "memory")
; #define PG8_WAIT_L(n) asm volatile("s_waitcnt lgkmcnt(" #n ")" ::: "memory")
; #define PG8_BAR __builtin_amdgcn_s_barrier()
; #define PG8_SCHED __builtin_amdgcn_sched_barrier(0)
; __device__ __forceinline__ float row_ssq(const float* part, int pitch, int n4, int row, int fq) {
;     f32x4 v = (f32x4){0.f, 0.f, 0.f, 0.f};
;     if (fq < n4) v = *(const f32x4*)(part + (size_t)row * pitch + 4 * fq);
; template <class Epi>
; __device__ __forceinline__ void gemm_phase(LAS unsigned char* lds, int wave_s, const Gemm g, const StaticOrder S, const Epi E) {
;     ...
;             PG8_LDB(B0, 0, 0); PG8_LDB(B1, 0, 1); PG8_SCHED; PG8_LDA(At, 0, 0); PG8_STAGE(PG8_SA(1, 1), a1 + hstepA, voffA);
;             PG8_WAIT_V(8); PG8_WAIT_L(0); PG8_BAR; PG8_MMA(0, 0, At, B0); PG8_MMA(0, 1, At, B1); PG8_BAR; PG8_SCHED;
.LBB0_165:
	s_cmp_eq_u32 s47, 6
	s_cbranch_scc0 .Lsq_ffn1up_skip
	v_readlane_b32 s100, v136, 0
	v_readlane_b32 s101, v137, 0
	s_lshl_b32 s6, s44, 14
	s_lshl_b32 s7, s92, 5
	s_add_u32 s6, s6, s7
	s_add_u32 s100, s100, s6
	s_addc_u32 s101, s101, 0
	s_add_i32 m0, s7, 0x24000
	v_lshlrev_b32_e32 v243, 4, v241
	s_nop 1
	global_load_lds_dwordx4 v243, s[100:101]
	global_load_lds_dwordx4 v243, s[100:101] offset:1024

; __device__ __forceinline__ float row_ssq(const float* part, int pitch, int n4, int row, int fq) {
;     f32x4 v = (f32x4){0.f, 0.f, 0.f, 0.f};
;     if (fq < n4) v = *(const f32x4*)(part + (size_t)row * pitch + 4 * fq);
;     float s = (v[0] + v[1]) + (v[2] + v[3]);
;     s += __shfl_xor(s, 16); s += __shfl_xor(s, 32);
;     return s;
; }
;     __device__ __forceinline__ void operator()(const f32x4 (&acc)[2][2][4][2], const Unit& u, int wr, int wc, int fr, int fq) const {
;         const int row0 = u.pm * BM + wr * 64 + fr, col0 = u.pn * 128 + wc * 32 + 8 * fq;
; #pragma unroll
;         for (int ai = 0; ai < 2; ++ai)
; #pragma unroll
;             for (int m = 0; m < 4; ++m) {
;                 const int row = row0 + ai * HALF + m * 16;
;                 const float rs = rsqrtf(row_ssq(ssq, 16, 4, row, fq) * (1.f / 1024.f) + EPS);
.LBB0_168:
	v_and_b32_e32 v145, 64, v241
	v_xor_b32_e32 v143, 16, v241
	v_add_u32_e32 v145, 64, v145
	v_cmp_lt_i32_e32 vcc, v143, v145
	v_lshl_add_u32 v144, s44, 8, v146
	v_lshl_or_b32 v142, s4, 7, v148
	v_cndmask_b32_e32 v143, v241, v143, vcc
	v_lshlrev_b32_e32 v150, 2, v143
	v_xor_b32_e32 v143, 32, v241
	v_cmp_lt_i32_e32 vcc, v143, v145
	v_ashrrev_i32_e32 v145, 31, v144
	v_and_b32_e32 v166, 48, v241
	v_lshl_add_u32 v166, v146, 6, v166
	v_add_u32_e32 v166, 0x24000, v166
	ds_read_b128 v[168:171], v166
	ds_read_b128 v[172:175], v166 offset:1024
	ds_read_b128 v[176:179], v166 offset:2048
	ds_read_b128 v[180:183], v166 offset:3072
	v_cndmask_b32_e32 v143, v241, v143, vcc
	v_lshlrev_b32_e32 v151, 2, v143
	ds_read_b128 v[184:187], v166 offset:8192
	ds_read_b128 v[188:191], v166 offset:9216
	ds_read_b128 v[192:195], v166 offset:10240
	ds_read_b128 v[196:199], v166 offset:11264
	v_ashrrev_i32_e32 v143, 31, v142
	v_lshl_add_u64 v[142:143], v[142:143], 1, s[96:97]
	s_movk_i32 s4, 0x1600
	s_mov_b64 s[24:25], -1
	s_waitcnt lgkmcnt(7)
	v_add_f32_e32 v168, v169, v168
	v_add_f32_e32 v170, v170, v171
	v_add_f32_e32 v168, v168, v170
	ds_bpermute_b32 v169, v150, v168
	s_waitcnt lgkmcnt(7)
	v_add_f32_e32 v172, v173, v172
	v_add_f32_e32 v174, v174, v175
	v_add_f32_e32 v172, v172, v174
	ds_bpermute_b32 v173, v150, v172
	s_waitcnt lgkmcnt(7)
	v_add_f32_e32 v176, v177, v176
	v_add_f32_e32 v178, v178, v179
	v_add_f32_e32 v176, v176, v178
	ds_bpermute_b32 v177, v150, v176
	s_waitcnt lgkmcnt(7)
	v_add_f32_e32 v180, v181, v180
	v_add_f32_e32 v182, v182, v183
	v_add_f32_e32 v180, v180, v182
	ds_bpermute_b32 v181, v150, v180
	s_waitcnt lgkmcnt(7)
	v_add_f32_e32 v184, v185, v184
	v_add_f32_e32 v186, v186, v187
	v_add_f32_e32 v184, v184, v186
	ds_bpermute_b32 v185, v150, v184
	s_waitcnt lgkmcnt(7)
	v_add_f32_e32 v188, v189, v188
	v_add_f32_e32 v190, v190, v191
	v_add_f32_e32 v188, v188, v190
	ds_bpermute_b32 v189, v150, v188
	s_waitcnt lgkmcnt(7)
	v_add_f32_e32 v192, v193, v192
	v_add_f32_e32 v194, v194, v195
	v_add_f32_e32 v192, v192, v194
	ds_bpermute_b32 v193, v150, v192
	s_waitcnt lgkmcnt(7)
	v_add_f32_e32 v196, v197, v196
	v_add_f32_e32 v198, v198, v199
	v_add_f32_e32 v196, v196, v198
	ds_bpermute_b32 v197, v150, v196
	s_waitcnt lgkmcnt(7)
	v_add_f32_e32 v168, v168, v169
	ds_bpermute_b32 v169, v151, v168
	s_waitcnt lgkmcnt(7)
	v_add_f32_e32 v172, v172, v173
	ds_bpermute_b32 v173, v151, v172
	s_waitcnt lgkmcnt(7)
	v_add_f32_e32 v176, v176, v177
	ds_bpermute_b32 v177, v151, v176
	s_waitcnt lgkmcnt(7)
	v_add_f32_e32 v180, v180, v181
	ds_bpermute_b32 v181, v151, v180
	s_waitcnt lgkmcnt(7)
	v_add_f32_e32 v184, v184, v185
	ds_bpermute_b32 v185, v151, v184
	s_waitcnt lgkmcnt(7)
	v_add_f32_e32 v188, v188, v189
	ds_bpermute_b32 v189, v151, v188
	s_waitcnt lgkmcnt(7)
	v_add_f32_e32 v192, v192, v193
	ds_bpermute_b32 v193, v151, v192
	s_waitcnt lgkmcnt(7)
	v_add_f32_e32 v196, v196, v197
	ds_bpermute_b32 v197, v151, v196
	s_waitcnt lgkmcnt(7)
	v_add_f32_e32 v168, v168, v169
	v_fmamk_f32 v168, v168, 0x3a800000, v239
	s_waitcnt lgkmcnt(6)
	v_add_f32_e32 v172, v172, v173
	v_fmamk_f32 v172, v172, 0x3a800000, v239
	s_waitcnt lgkmcnt(5)
	v_add_f32_e32 v176, v176, v177
	v_fmamk_f32 v176, v176, 0x3a800000, v239
	s_waitcnt lgkmcnt(4)
	v_add_f32_e32 v180, v180, v181
	v_fmamk_f32 v180, v180, 0x3a800000, v239
	s_waitcnt lgkmcnt(3)
	v_add_f32_e32 v184, v184, v185
	v_fmamk_f32 v184, v184, 0x3a800000, v239
	s_waitcnt lgkmcnt(2)
	v_add_f32_e32 v188, v188, v189
	v_fmamk_f32 v188, v188, 0x3a800000, v239
	s_waitcnt lgkmcnt(1)
	v_add_f32_e32 v192, v192, v193
	v_fmamk_f32 v192, v192, 0x3a800000, v239
	s_waitcnt lgkmcnt(0)
	v_add_f32_e32 v196, v196, v197
	v_fmamk_f32 v196, v196, 0x3a800000, v239
	v_cmp_gt_f32_e32 vcc, s55, v168
	v_mul_f32_e32 v169, 0x4b800000, v168
	s_nop 0
	v_cndmask_b32_e32 v168, v168, v169, vcc
	v_rsq_f32_e32 v168, v168
	s_nop 0
	v_mul_f32_e32 v169, 0x45800000, v168
	v_cndmask_b32_e32 v158, v168, v169, vcc
	v_cmp_gt_f32_e32 vcc, s55, v172
	v_mul_f32_e32 v173, 0x4b800000, v172
	s_nop 0
	v_cndmask_b32_e32 v172, v172, v173, vcc
	v_rsq_f32_e32 v172, v172
	s_nop 0
	v_mul_f32_e32 v173, 0x45800000, v172
	v_cndmask_b32_e32 v159, v172, v173, vcc
	v_cmp_gt_f32_e32 vcc, s55, v176
	v_mul_f32_e32 v177, 0x4b800000, v176
	s_nop 0
	v_cndmask_b32_e32 v176, v176, v177, vcc
	v_rsq_f32_e32 v176, v176
	s_nop 0
	v_mul_f32_e32 v177, 0x45800000, v176
	v_cndmask_b32_e32 v160, v176, v177, vcc
	v_cmp_gt_f32_e32 vcc, s55, v180
	v_mul_f32_e32 v181, 0x4b800000, v180
	s_nop 0
	v_cndmask_b32_e32 v180, v180, v181, vcc
	v_rsq_f32_e32 v180, v180
	s_nop 0
	v_mul_f32_e32 v181, 0x45800000, v180
	v_cndmask_b32_e32 v161, v180, v181, vcc
	v_cmp_gt_f32_e32 vcc, s55, v184
	v_mul_f32_e32 v185, 0x4b800000, v184
	s_nop 0
	v_cndmask_b32_e32 v184, v184, v185, vcc
	v_rsq_f32_e32 v184, v184
	s_nop 0
	v_mul_f32_e32 v185, 0x45800000, v184
	v_cndmask_b32_e32 v162, v184, v185, vcc
	v_cmp_gt_f32_e32 vcc, s55, v188
	v_mul_f32_e32 v189, 0x4b800000, v188
	s_nop 0
	v_cndmask_b32_e32 v188, v188, v189, vcc
	v_rsq_f32_e32 v188, v188
	s_nop 0
	v_mul_f32_e32 v189, 0x45800000, v188
	v_cndmask_b32_e32 v163, v188, v189, vcc
	v_cmp_gt_f32_e32 vcc, s55, v192
	v_mul_f32_e32 v193, 0x4b800000, v192
	s_nop 0
	v_cndmask_b32_e32 v192, v192, v193, vcc
	v_rsq_f32_e32 v192, v192
	s_nop 0
	v_mul_f32_e32 v193, 0x45800000, v192
	v_cndmask_b32_e32 v164, v192, v193, vcc
	v_cmp_gt_f32_e32 vcc, s55, v196
	v_mul_f32_e32 v197, 0x4b800000, v196
	s_nop 0
	v_cndmask_b32_e32 v196, v196, v197, vcc
	v_rsq_f32_e32 v196, v196
	s_nop 0
	v_mul_f32_e32 v197, 0x45800000, v196
	v_cndmask_b32_e32 v165, v196, v197, vcc
	v_mov_b32_e32 v152, v158
; __device__ __forceinline__ unsigned pk2(float lo, float hi) { f32x2_t v = {lo, hi}; bf16x2_t b = __builtin_convertvector(v, bf16x2_t); return __builtin_bit_cast(unsigned, b); }
; __device__ __forceinline__ float fast_sigmoid(float x) { return __builtin_amdgcn_rcpf(1.f + __expf(-x)); }
;     __device__ __forceinline__ void operator()(const f32x4 (&acc)[2][2][4][2], const Unit& u, int wr, int wc, int fr, int fq) const {
;     ...
;                 for (int n = 0; n < 2; ++n)
; #pragma unroll
;                     for (int e = 0; e < 4; ++e) { const float gv = acc[ai][0][m][n][e] * rs, uv = acc[ai][1][m][n][e] * rs; r[n * 4 + e] = gv * fast_sigmoid(gv) * uv; }
;                 u32x4 w; w.x = pk2(r[0], r[1]); w.y = pk2(r[2], r[3]); w.z = pk2(r[4], r[5]); w.w = pk2(r[6], r[7]);
;                 *(u32x4*)(O + (size_t)row * DFF + col0) = w;
	v_pk_mul_f32 v[126:127], v[126:127], v[152:153] op_sel_hi:[1,0]
	v_pk_mul_f32 v[118:119], v[118:119], v[152:153] op_sel_hi:[1,0]
	v_mul_f32_e32 v145, 0xbfb8aa3b, v126
	v_exp_f32_e32 v145, v145
	v_pk_mul_f32 v[120:121], v[120:121], v[152:153] op_sel_hi:[1,0]
	v_pk_mul_f32 v[122:123], v[122:123], v[152:153] op_sel_hi:[1,0]
	v_pk_mul_f32 v[114:115], v[114:115], v[152:153] op_sel_hi:[1,0]
	v_add_f32_e32 v145, 1.0, v145
	v_rcp_f32_e32 v154, v145
	v_mul_f32_e32 v145, 0xbfb8aa3b, v127
	v_exp_f32_e32 v145, v145
	v_pk_mul_f32 v[116:117], v[116:117], v[152:153] op_sel_hi:[1,0]
	v_add_f32_e32 v145, 1.0, v145
	v_rcp_f32_e32 v155, v145
	s_nop 0
	v_pk_mul_f32 v[126:127], v[126:127], v[154:155]
	s_nop 0
	v_pk_mul_f32 v[118:119], v[118:119], v[126:127]
	v_pk_mul_f32 v[126:127], v[128:129], v[152:153] op_sel_hi:[1,0]
	s_nop 0
	v_mul_f32_e32 v128, 0xbfb8aa3b, v126
	v_mul_f32_e32 v129, 0xbfb8aa3b, v127
	v_exp_f32_e32 v128, v128
	v_exp_f32_e32 v129, v129
	v_add_f32_e32 v128, 1.0, v128
	v_add_f32_e32 v129, 1.0, v129
	v_rcp_f32_e32 v128, v128
	v_rcp_f32_e32 v129, v129
	s_nop 0
	v_pk_mul_f32 v[126:127], v[126:127], v[128:129]
	s_nop 0
	v_pk_mul_f32 v[120:121], v[120:121], v[126:127]
	v_mul_f32_e32 v126, 0xbfb8aa3b, v122
	v_mul_f32_e32 v127, 0xbfb8aa3b, v123
	v_exp_f32_e32 v126, v126
	v_exp_f32_e32 v127, v127
	v_add_f32_e32 v126, 1.0, v126
	v_add_f32_e32 v127, 1.0, v127
	v_rcp_f32_e32 v126, v126
	v_rcp_f32_e32 v127, v127
	s_nop 0
	v_pk_mul_f32 v[122:123], v[122:123], v[126:127]
	s_nop 0
	v_pk_mul_f32 v[122:123], v[114:115], v[122:123]
	v_pk_mul_f32 v[114:115], v[124:125], v[152:153] op_sel_hi:[1,0]
	s_nop 0
	v_mul_f32_e32 v124, 0xbfb8aa3b, v114
	v_mul_f32_e32 v125, 0xbfb8aa3b, v115
	v_exp_f32_e32 v124, v124
	v_exp_f32_e32 v125, v125
	v_add_f32_e32 v124, 1.0, v124
	v_add_f32_e32 v125, 1.0, v125
	v_rcp_f32_e32 v124, v124
	v_rcp_f32_e32 v125, v125
	s_nop 0
	v_pk_mul_f32 v[114:115], v[114:115], v[124:125]
	s_nop 0
	v_pk_mul_f32 v[124:125], v[116:117], v[114:115]
	v_cvt_pk_bf16_f32 v114, v118, v119
	v_cvt_pk_bf16_f32 v115, v120, v121
	v_cvt_pk_bf16_f32 v116, v122, v123
	v_cvt_pk_bf16_f32 v117, v124, v125
	v_mad_i64_i32 v[118:119], s[6:7], v144, s4, v[142:143]
	global_store_dwordx4 v[118:119], v[114:117], off
	s_nop 1
	v_or_b32_e32 v114, 16, v144
	v_mov_b32_e32 v116, v159
	v_pk_mul_f32 v[110:111], v[110:111], v[116:117] op_sel_hi:[1,0]
	v_pk_mul_f32 v[102:103], v[102:103], v[116:117] op_sel_hi:[1,0]
	v_mul_f32_e32 v115, 0xbfb8aa3b, v110
	v_exp_f32_e32 v115, v115
	v_pk_mul_f32 v[104:105], v[104:105], v[116:117] op_sel_hi:[1,0]
	v_pk_mul_f32 v[106:107], v[106:107], v[116:117] op_sel_hi:[1,0]
	v_pk_mul_f32 v[98:99], v[98:99], v[116:117] op_sel_hi:[1,0]
	v_add_f32_e32 v115, 1.0, v115
	v_rcp_f32_e32 v118, v115
	v_mul_f32_e32 v115, 0xbfb8aa3b, v111
	v_exp_f32_e32 v115, v115
	v_pk_mul_f32 v[100:101], v[100:101], v[116:117] op_sel_hi:[1,0]
	v_add_f32_e32 v115, 1.0, v115
	v_rcp_f32_e32 v119, v115
	s_nop 0
	v_pk_mul_f32 v[110:111], v[110:111], v[118:119]
	s_nop 0
	v_pk_mul_f32 v[102:103], v[102:103], v[110:111]
	v_pk_mul_f32 v[110:111], v[112:113], v[116:117] op_sel_hi:[1,0]
	s_nop 0
	v_mul_f32_e32 v112, 0xbfb8aa3b, v110
	v_mul_f32_e32 v113, 0xbfb8aa3b, v111
	v_exp_f32_e32 v112, v112
	v_exp_f32_e32 v113, v113
	v_add_f32_e32 v112, 1.0, v112
	v_add_f32_e32 v113, 1.0, v113
	v_rcp_f32_e32 v112, v112
	v_rcp_f32_e32 v113, v113
	s_nop 0
	v_pk_mul_f32 v[110:111], v[110:111], v[112:113]
	s_nop 0
	v_pk_mul_f32 v[104:105], v[104:105], v[110:111]
	v_mul_f32_e32 v110, 0xbfb8aa3b, v106
	v_mul_f32_e32 v111, 0xbfb8aa3b, v107
	v_exp_f32_e32 v110, v110
	v_exp_f32_e32 v111, v111
	v_add_f32_e32 v110, 1.0, v110
	v_add_f32_e32 v111, 1.0, v111
	v_rcp_f32_e32 v110, v110
	v_rcp_f32_e32 v111, v111
	s_nop 0
	v_pk_mul_f32 v[106:107], v[106:107], v[110:111]
	s_nop 0
	v_pk_mul_f32 v[106:107], v[98:99], v[106:107]
	v_pk_mul_f32 v[98:99], v[108:109], v[116:117] op_sel_hi:[1,0]
	s_nop 0
	v_mul_f32_e32 v108, 0xbfb8aa3b, v98
	v_mul_f32_e32 v109, 0xbfb8aa3b, v99
	v_exp_f32_e32 v108, v108
	v_exp_f32_e32 v109, v109
	v_add_f32_e32 v108, 1.0, v108
	v_add_f32_e32 v109, 1.0, v109
	v_rcp_f32_e32 v108, v108
	v_rcp_f32_e32 v109, v109
	s_nop 0
	v_pk_mul_f32 v[98:99], v[98:99], v[108:109]
	s_nop 0
	v_pk_mul_f32 v[108:109], v[100:101], v[98:99]
	v_cvt_pk_bf16_f32 v98, v102, v103
	v_cvt_pk_bf16_f32 v99, v104, v105
	v_cvt_pk_bf16_f32 v100, v106, v107
	v_cvt_pk_bf16_f32 v101, v108, v109
	v_mad_i64_i32 v[102:103], s[6:7], v114, s4, v[142:143]
	global_store_dwordx4 v[102:103], v[98:101], off
	s_nop 1
	v_or_b32_e32 v98, 32, v144
	v_mov_b32_e32 v100, v160
	v_pk_mul_f32 v[94:95], v[94:95], v[100:101] op_sel_hi:[1,0]
	v_pk_mul_f32 v[86:87], v[86:87], v[100:101] op_sel_hi:[1,0]
	v_mul_f32_e32 v99, 0xbfb8aa3b, v94
	v_exp_f32_e32 v99, v99
	v_pk_mul_f32 v[88:89], v[88:89], v[100:101] op_sel_hi:[1,0]
	v_pk_mul_f32 v[90:91], v[90:91], v[100:101] op_sel_hi:[1,0]
	v_pk_mul_f32 v[82:83], v[82:83], v[100:101] op_sel_hi:[1,0]
	v_add_f32_e32 v99, 1.0, v99
	v_rcp_f32_e32 v102, v99
	v_mul_f32_e32 v99, 0xbfb8aa3b, v95
	v_exp_f32_e32 v99, v99
	v_pk_mul_f32 v[84:85], v[84:85], v[100:101] op_sel_hi:[1,0]
	v_add_f32_e32 v99, 1.0, v99
	v_rcp_f32_e32 v103, v99
	s_nop 0
	v_pk_mul_f32 v[94:95], v[94:95], v[102:103]
	s_nop 0
	v_pk_mul_f32 v[86:87], v[86:87], v[94:95]
	v_pk_mul_f32 v[94:95], v[96:97], v[100:101] op_sel_hi:[1,0]
	s_nop 0
	v_mul_f32_e32 v96, 0xbfb8aa3b, v94
	v_mul_f32_e32 v97, 0xbfb8aa3b, v95
	v_exp_f32_e32 v96, v96
	v_exp_f32_e32 v97, v97
	v_add_f32_e32 v96, 1.0, v96
	v_add_f32_e32 v97, 1.0, v97
	v_rcp_f32_e32 v96, v96
	v_rcp_f32_e32 v97, v97
	s_nop 0
	v_pk_mul_f32 v[94:95], v[94:95], v[96:97]
	s_nop 0
	v_pk_mul_f32 v[88:89], v[88:89], v[94:95]
; __device__ __forceinline__ unsigned pk2(float lo, float hi) { f32x2_t v = {lo, hi}; bf16x2_t b = __builtin_convertvector(v, bf16x2_t); return __builtin_bit_cast(unsigned, b); }
; __device__ __forceinline__ float fast_sigmoid(float x) { return __builtin_amdgcn_rcpf(1.f + __expf(-x)); }
;     __device__ __forceinline__ void operator()(const f32x4 (&acc)[2][2][4][2], const Unit& u, int wr, int wc, int fr, int fq) const {
;     ...
;                 for (int n = 0; n < 2; ++n)
; #pragma unroll
;                     for (int e = 0; e < 4; ++e) { const float gv = acc[ai][0][m][n][e] * rs, uv = acc[ai][1][m][n][e] * rs; r[n * 4 + e] = gv * fast_sigmoid(gv) * uv; }
;                 u32x4 w; w.x = pk2(r[0], r[1]); w.y = pk2(r[2], r[3]); w.z = pk2(r[4], r[5]); w.w = pk2(r[6], r[7]);
;                 *(u32x4*)(O + (size_t)row * DFF + col0) = w;
	v_mul_f32_e32 v94, 0xbfb8aa3b, v90
	v_mul_f32_e32 v95, 0xbfb8aa3b, v91
	v_exp_f32_e32 v94, v94
	v_exp_f32_e32 v95, v95
	v_add_f32_e32 v94, 1.0, v94
	v_add_f32_e32 v95, 1.0, v95
	v_rcp_f32_e32 v94, v94
	v_rcp_f32_e32 v95, v95
	s_nop 0
	v_pk_mul_f32 v[90:91], v[90:91], v[94:95]
	s_nop 0
	v_pk_mul_f32 v[90:91], v[82:83], v[90:91]
	v_pk_mul_f32 v[82:83], v[92:93], v[100:101] op_sel_hi:[1,0]
	s_nop 0
	v_mul_f32_e32 v92, 0xbfb8aa3b, v82
	v_mul_f32_e32 v93, 0xbfb8aa3b, v83
	v_exp_f32_e32 v92, v92
	v_exp_f32_e32 v93, v93
	v_add_f32_e32 v92, 1.0, v92
	v_add_f32_e32 v93, 1.0, v93
	v_rcp_f32_e32 v92, v92
	v_rcp_f32_e32 v93, v93
	s_nop 0
	v_pk_mul_f32 v[82:83], v[82:83], v[92:93]
	s_nop 0
	v_pk_mul_f32 v[92:93], v[84:85], v[82:83]
	v_cvt_pk_bf16_f32 v82, v86, v87
	v_cvt_pk_bf16_f32 v83, v88, v89
	v_cvt_pk_bf16_f32 v84, v90, v91
	v_cvt_pk_bf16_f32 v85, v92, v93
	v_mad_i64_i32 v[86:87], s[6:7], v98, s4, v[142:143]
	global_store_dwordx4 v[86:87], v[82:85], off
	s_nop 1
	v_or_b32_e32 v82, 48, v144
	v_mov_b32_e32 v84, v161
	v_pk_mul_f32 v[78:79], v[78:79], v[84:85] op_sel_hi:[1,0]
	v_pk_mul_f32 v[70:71], v[70:71], v[84:85] op_sel_hi:[1,0]
	v_mul_f32_e32 v83, 0xbfb8aa3b, v78
	v_exp_f32_e32 v83, v83
	v_pk_mul_f32 v[72:73], v[72:73], v[84:85] op_sel_hi:[1,0]
	v_pk_mul_f32 v[74:75], v[74:75], v[84:85] op_sel_hi:[1,0]
	v_pk_mul_f32 v[66:67], v[66:67], v[84:85] op_sel_hi:[1,0]
	v_add_f32_e32 v83, 1.0, v83
	v_rcp_f32_e32 v86, v83
	v_mul_f32_e32 v83, 0xbfb8aa3b, v79
	v_exp_f32_e32 v83, v83
	v_pk_mul_f32 v[68:69], v[68:69], v[84:85] op_sel_hi:[1,0]
	v_add_f32_e32 v83, 1.0, v83
	v_rcp_f32_e32 v87, v83
	s_nop 0
	v_pk_mul_f32 v[78:79], v[78:79], v[86:87]
	s_nop 0
	v_pk_mul_f32 v[70:71], v[70:71], v[78:79]
	v_pk_mul_f32 v[78:79], v[80:81], v[84:85] op_sel_hi:[1,0]
	s_nop 0
	v_mul_f32_e32 v80, 0xbfb8aa3b, v78
	v_mul_f32_e32 v81, 0xbfb8aa3b, v79
	v_exp_f32_e32 v80, v80
	v_exp_f32_e32 v81, v81
	v_add_f32_e32 v80, 1.0, v80
	v_add_f32_e32 v81, 1.0, v81
	v_rcp_f32_e32 v80, v80
	v_rcp_f32_e32 v81, v81
	s_nop 0
	v_pk_mul_f32 v[78:79], v[78:79], v[80:81]
	s_nop 0
	v_pk_mul_f32 v[72:73], v[72:73], v[78:79]
	v_mul_f32_e32 v78, 0xbfb8aa3b, v74
	v_mul_f32_e32 v79, 0xbfb8aa3b, v75
	v_exp_f32_e32 v78, v78
	v_exp_f32_e32 v79, v79
	v_add_f32_e32 v78, 1.0, v78
	v_add_f32_e32 v79, 1.0, v79
	v_rcp_f32_e32 v78, v78
	v_rcp_f32_e32 v79, v79
	s_nop 0
	v_pk_mul_f32 v[74:75], v[74:75], v[78:79]
	s_nop 0
	v_pk_mul_f32 v[74:75], v[66:67], v[74:75]
	v_pk_mul_f32 v[66:67], v[76:77], v[84:85] op_sel_hi:[1,0]
	s_nop 0
	v_mul_f32_e32 v76, 0xbfb8aa3b, v66
	v_mul_f32_e32 v77, 0xbfb8aa3b, v67
	v_exp_f32_e32 v76, v76
	v_exp_f32_e32 v77, v77
	v_add_f32_e32 v76, 1.0, v76
	v_add_f32_e32 v77, 1.0, v77
	v_rcp_f32_e32 v76, v76
	v_rcp_f32_e32 v77, v77
	s_nop 0
	v_pk_mul_f32 v[66:67], v[66:67], v[76:77]
	s_nop 0
	v_pk_mul_f32 v[76:77], v[68:69], v[66:67]
	v_cvt_pk_bf16_f32 v66, v70, v71
	v_cvt_pk_bf16_f32 v67, v72, v73
	v_cvt_pk_bf16_f32 v68, v74, v75
	v_cvt_pk_bf16_f32 v69, v76, v77
	v_mad_i64_i32 v[70:71], s[6:7], v82, s4, v[142:143]
	global_store_dwordx4 v[70:71], v[66:69], off
	s_nop 1
	v_add_u32_e32 v66, 0x80, v144
	v_mov_b32_e32 v68, v162
	v_pk_mul_f32 v[62:63], v[62:63], v[68:69] op_sel_hi:[1,0]
	v_pk_mul_f32 v[54:55], v[54:55], v[68:69] op_sel_hi:[1,0]
	v_mul_f32_e32 v67, 0xbfb8aa3b, v62
	v_exp_f32_e32 v67, v67
	v_pk_mul_f32 v[56:57], v[56:57], v[68:69] op_sel_hi:[1,0]
	v_pk_mul_f32 v[58:59], v[58:59], v[68:69] op_sel_hi:[1,0]
	v_pk_mul_f32 v[50:51], v[50:51], v[68:69] op_sel_hi:[1,0]
	v_add_f32_e32 v67, 1.0, v67
	v_rcp_f32_e32 v70, v67
	v_mul_f32_e32 v67, 0xbfb8aa3b, v63
	v_exp_f32_e32 v67, v67
	v_pk_mul_f32 v[52:53], v[52:53], v[68:69] op_sel_hi:[1,0]
	v_add_f32_e32 v67, 1.0, v67
	v_rcp_f32_e32 v71, v67
	s_nop 0
	v_pk_mul_f32 v[62:63], v[62:63], v[70:71]
	s_nop 0
	v_pk_mul_f32 v[54:55], v[54:55], v[62:63]
	v_pk_mul_f32 v[62:63], v[64:65], v[68:69] op_sel_hi:[1,0]
	s_nop 0
	v_mul_f32_e32 v64, 0xbfb8aa3b, v62
	v_mul_f32_e32 v65, 0xbfb8aa3b, v63
	v_exp_f32_e32 v64, v64
	v_exp_f32_e32 v65, v65
	v_add_f32_e32 v64, 1.0, v64
	v_add_f32_e32 v65, 1.0, v65
	v_rcp_f32_e32 v64, v64
	v_rcp_f32_e32 v65, v65
	s_nop 0
	v_pk_mul_f32 v[62:63], v[62:63], v[64:65]
	s_nop 0
	v_pk_mul_f32 v[56:57], v[56:57], v[62:63]
	v_mul_f32_e32 v62, 0xbfb8aa3b, v58
	v_mul_f32_e32 v63, 0xbfb8aa3b, v59
	v_exp_f32_e32 v62, v62
	v_exp_f32_e32 v63, v63
	v_add_f32_e32 v62, 1.0, v62
	v_add_f32_e32 v63, 1.0, v63
	v_rcp_f32_e32 v62, v62
	v_rcp_f32_e32 v63, v63
	s_nop 0
	v_pk_mul_f32 v[58:59], v[58:59], v[62:63]
	s_nop 0
	v_pk_mul_f32 v[58:59], v[50:51], v[58:59]
	v_pk_mul_f32 v[50:51], v[60:61], v[68:69] op_sel_hi:[1,0]
	s_nop 0
	v_mul_f32_e32 v60, 0xbfb8aa3b, v50
	v_mul_f32_e32 v61, 0xbfb8aa3b, v51
	v_exp_f32_e32 v60, v60
	v_exp_f32_e32 v61, v61
	v_add_f32_e32 v60, 1.0, v60
	v_add_f32_e32 v61, 1.0, v61
	v_rcp_f32_e32 v60, v60
	v_rcp_f32_e32 v61, v61
	s_nop 0
	v_pk_mul_f32 v[50:51], v[50:51], v[60:61]
	s_nop 0
	v_pk_mul_f32 v[60:61], v[52:53], v[50:51]
	v_cvt_pk_bf16_f32 v50, v54, v55
	v_cvt_pk_bf16_f32 v51, v56, v57
	v_cvt_pk_bf16_f32 v52, v58, v59
	v_cvt_pk_bf16_f32 v53, v60, v61
	v_mad_i64_i32 v[54:55], s[6:7], v66, s4, v[142:143]
	global_store_dwordx4 v[54:55], v[50:53], off
	s_nop 1
	v_add_u32_e32 v50, 0x90, v144
	v_mov_b32_e32 v52, v163
	v_pk_mul_f32 v[46:47], v[46:47], v[52:53] op_sel_hi:[1,0]
	v_pk_mul_f32 v[38:39], v[38:39], v[52:53] op_sel_hi:[1,0]
	v_mul_f32_e32 v51, 0xbfb8aa3b, v46
	v_exp_f32_e32 v51, v51
	v_pk_mul_f32 v[40:41], v[40:41], v[52:53] op_sel_hi:[1,0]
	v_pk_mul_f32 v[42:43], v[42:43], v[52:53] op_sel_hi:[1,0]
	v_pk_mul_f32 v[34:35], v[34:35], v[52:53] op_sel_hi:[1,0]
	v_add_f32_e32 v51, 1.0, v51
	v_rcp_f32_e32 v54, v51
; template <class Epi>
; __device__ __forceinline__ void gemm_phase(LAS unsigned char* lds, int wave_s, const Gemm g, const StaticOrder S, const Epi E) {
;     ...
;     for (;;) {
;         const bool has_next = S.next(ui + 1, nxt);
;         const char* nA = has_next ? (const char*)g.A + (size_t)nxt.pm * tstepA : cA; const char* nB = has_next ? (const char*)g.Bt + (size_t)nxt.pn * tstepB : cB;
;         for (int t = 0; t < nt; t += 2) {
;             const bool last = (t == nt - 2);
;             const char* a1 = cA + (size_t)(t + 1) * kstep;
;             const char* a2 = last ? nA : cA + (size_t)(t + 2) * kstep; const char* b2 = last ? nB : cB + (size_t)(t + 2) * kstep;
;             const char* a3 = a2 + kstep; const char* b3 = b2 + kstep;
;             PG8_LDB(B0, 0, 0); PG8_LDB(B1, 0, 1); PG8_SCHED; PG8_LDA(At, 0, 0); PG8_STAGE(PG8_SA(1, 1), a1 + hstepA, voffA);
;             PG8_WAIT_V(8); PG8_WAIT_L(0); PG8_BAR; PG8_MMA(0, 0, At, B0); PG8_MMA(0, 1, At, B1); PG8_BAR; PG8_SCHED;
;             PG8_LDA(At, 0, 1); PG8_STAGE(PG8_SB(0, 0), b2, voffB); PG8_STAGE(PG8_SB(0, 1), b2 + hstepB, voffB); PG8_STAGE(PG8_SA(0, 0), a2, voffA);
;             PG8_WAIT_V(8); PG8_WAIT_L(0); PG8_BAR; PG8_MMA(1, 0, At, B0); PG8_MMA(1, 1, At, B1); PG8_BAR; PG8_SCHED;
;             PG8_LDB(B0, 1, 0); PG8_LDB(B1, 1, 1); PG8_SCHED; PG8_LDA(At, 1, 0); PG8_STAGE(PG8_SA(0, 1), a2 + hstepA, voffA);
;             PG8_WAIT_V(8); PG8_WAIT_L(0); PG8_BAR; PG8_MMA(0, 0, At, B0); PG8_MMA(0, 1, At, B1); PG8_BAR; PG8_SCHED;
;             PG8_LDA(At, 1, 1); PG8_STAGE(PG8_SB(1, 0), b3, voffB); PG8_STAGE(PG8_SB(1, 1), b3 + hstepB, voffB); PG8_STAGE(PG8_SA(1, 0), a3, voffA);
;             PG8_WAIT_V(8); PG8_WAIT_L(0); PG8_BAR; PG8_MMA(1, 0, At, B0); PG8_MMA(1, 1, At, B1); PG8_BAR; PG8_SCHED;
;         }
;         if (wr == 0) PG8_BAR;
;     __device__ __forceinline__ void operator()(const f32x4 (&acc)[2][2][4][2], const Unit& u, int wr, int wc, int fr, int fq) const {
;     ...
;                 for (int n = 0; n < 2; ++n)
; #pragma unroll
;                     for (int e = 0; e < 4; ++e) { const float gv = acc[ai][0][m][n][e] * rs, uv = acc[ai][1][m][n][e] * rs; r[n * 4 + e] = gv * fast_sigmoid(gv) * uv; }
;                 u32x4 w; w.x = pk2(r[0], r[1]); w.y = pk2(r[2], r[3]); w.z = pk2(r[4], r[5]); w.w = pk2(r[6], r[7]);
;                 *(u32x4*)(O + (size_t)row * DFF + col0) = w;
	v_mul_f32_e32 v51, 0xbfb8aa3b, v47
	v_exp_f32_e32 v51, v51
	v_pk_mul_f32 v[36:37], v[36:37], v[52:53] op_sel_hi:[1,0]
	v_add_f32_e32 v51, 1.0, v51
	v_rcp_f32_e32 v55, v51
	s_nop 0
	v_pk_mul_f32 v[46:47], v[46:47], v[54:55]
	s_nop 0
	v_pk_mul_f32 v[38:39], v[38:39], v[46:47]
	v_pk_mul_f32 v[46:47], v[48:49], v[52:53] op_sel_hi:[1,0]
	s_nop 0
	v_mul_f32_e32 v48, 0xbfb8aa3b, v46
	v_mul_f32_e32 v49, 0xbfb8aa3b, v47
	v_exp_f32_e32 v48, v48
	v_exp_f32_e32 v49, v49
	v_add_f32_e32 v48, 1.0, v48
	v_add_f32_e32 v49, 1.0, v49
	v_rcp_f32_e32 v48, v48
	v_rcp_f32_e32 v49, v49
	s_nop 0
	v_pk_mul_f32 v[46:47], v[46:47], v[48:49]
	s_nop 0
	v_pk_mul_f32 v[40:41], v[40:41], v[46:47]
	v_mul_f32_e32 v46, 0xbfb8aa3b, v42
	v_mul_f32_e32 v47, 0xbfb8aa3b, v43
	v_exp_f32_e32 v46, v46
	v_exp_f32_e32 v47, v47
	v_add_f32_e32 v46, 1.0, v46
	v_add_f32_e32 v47, 1.0, v47
	v_rcp_f32_e32 v46, v46
	v_rcp_f32_e32 v47, v47
	s_nop 0
	v_pk_mul_f32 v[42:43], v[42:43], v[46:47]
	s_nop 0
	v_pk_mul_f32 v[42:43], v[34:35], v[42:43]
	v_pk_mul_f32 v[34:35], v[44:45], v[52:53] op_sel_hi:[1,0]
	s_nop 0
	v_mul_f32_e32 v44, 0xbfb8aa3b, v34
	v_mul_f32_e32 v45, 0xbfb8aa3b, v35
	v_exp_f32_e32 v44, v44
	v_exp_f32_e32 v45, v45
	v_add_f32_e32 v44, 1.0, v44
	v_add_f32_e32 v45, 1.0, v45
	v_rcp_f32_e32 v44, v44
	v_rcp_f32_e32 v45, v45
	s_nop 0
	v_pk_mul_f32 v[34:35], v[34:35], v[44:45]
	s_nop 0
	v_pk_mul_f32 v[44:45], v[36:37], v[34:35]
	v_cvt_pk_bf16_f32 v34, v38, v39
	v_cvt_pk_bf16_f32 v35, v40, v41
	v_cvt_pk_bf16_f32 v36, v42, v43
	v_cvt_pk_bf16_f32 v37, v44, v45
	v_mad_i64_i32 v[38:39], s[6:7], v50, s4, v[142:143]
	global_store_dwordx4 v[38:39], v[34:37], off
	s_nop 1
	v_add_u32_e32 v34, 0xa0, v144
	v_mov_b32_e32 v36, v164
	v_pk_mul_f32 v[30:31], v[30:31], v[36:37] op_sel_hi:[1,0]
	v_pk_mul_f32 v[22:23], v[22:23], v[36:37] op_sel_hi:[1,0]
	v_mul_f32_e32 v35, 0xbfb8aa3b, v30
	v_exp_f32_e32 v35, v35
	v_pk_mul_f32 v[24:25], v[24:25], v[36:37] op_sel_hi:[1,0]
	v_pk_mul_f32 v[26:27], v[26:27], v[36:37] op_sel_hi:[1,0]
	v_pk_mul_f32 v[18:19], v[18:19], v[36:37] op_sel_hi:[1,0]
	v_add_f32_e32 v35, 1.0, v35
	v_rcp_f32_e32 v38, v35
	v_mul_f32_e32 v35, 0xbfb8aa3b, v31
	v_exp_f32_e32 v35, v35
	v_pk_mul_f32 v[20:21], v[20:21], v[36:37] op_sel_hi:[1,0]
	v_add_f32_e32 v35, 1.0, v35
	v_rcp_f32_e32 v39, v35
	s_nop 0
	v_pk_mul_f32 v[30:31], v[30:31], v[38:39]
	s_nop 0
	v_pk_mul_f32 v[22:23], v[22:23], v[30:31]
	v_pk_mul_f32 v[30:31], v[32:33], v[36:37] op_sel_hi:[1,0]
	s_nop 0
	v_mul_f32_e32 v32, 0xbfb8aa3b, v30
	v_mul_f32_e32 v33, 0xbfb8aa3b, v31
	v_exp_f32_e32 v32, v32
	v_exp_f32_e32 v33, v33
	v_add_f32_e32 v32, 1.0, v32
	v_add_f32_e32 v33, 1.0, v33
	v_rcp_f32_e32 v32, v32
	v_rcp_f32_e32 v33, v33
	s_nop 0
	v_pk_mul_f32 v[30:31], v[30:31], v[32:33]
	s_nop 0
	v_pk_mul_f32 v[24:25], v[24:25], v[30:31]
	v_mul_f32_e32 v30, 0xbfb8aa3b, v26
	v_mul_f32_e32 v31, 0xbfb8aa3b, v27
	v_exp_f32_e32 v30, v30
	v_exp_f32_e32 v31, v31
	v_add_f32_e32 v30, 1.0, v30
	v_add_f32_e32 v31, 1.0, v31
	v_rcp_f32_e32 v30, v30
	v_rcp_f32_e32 v31, v31
	s_nop 0
	v_pk_mul_f32 v[26:27], v[26:27], v[30:31]
	s_nop 0
	v_pk_mul_f32 v[26:27], v[18:19], v[26:27]
	v_pk_mul_f32 v[18:19], v[28:29], v[36:37] op_sel_hi:[1,0]
	s_nop 0
	v_mul_f32_e32 v28, 0xbfb8aa3b, v18
	v_mul_f32_e32 v29, 0xbfb8aa3b, v19
	v_exp_f32_e32 v28, v28
	v_exp_f32_e32 v29, v29
	v_add_f32_e32 v28, 1.0, v28
	v_add_f32_e32 v29, 1.0, v29
	v_rcp_f32_e32 v28, v28
	v_rcp_f32_e32 v29, v29
	s_nop 0
	v_pk_mul_f32 v[18:19], v[18:19], v[28:29]
	s_nop 0
	v_pk_mul_f32 v[28:29], v[20:21], v[18:19]
	v_cvt_pk_bf16_f32 v18, v22, v23
	v_cvt_pk_bf16_f32 v19, v24, v25
	v_cvt_pk_bf16_f32 v20, v26, v27
	v_cvt_pk_bf16_f32 v21, v28, v29
	v_mad_i64_i32 v[22:23], s[6:7], v34, s4, v[142:143]
	global_store_dwordx4 v[22:23], v[18:21], off
	s_nop 1
	v_add_u32_e32 v18, 0xb0, v144
	v_mov_b32_e32 v20, v165
	v_pk_mul_f32 v[14:15], v[14:15], v[20:21] op_sel_hi:[1,0]
	v_pk_mul_f32 v[6:7], v[6:7], v[20:21] op_sel_hi:[1,0]
	v_mul_f32_e32 v19, 0xbfb8aa3b, v14
	v_exp_f32_e32 v19, v19
	v_pk_mul_f32 v[8:9], v[8:9], v[20:21] op_sel_hi:[1,0]
	v_pk_mul_f32 v[10:11], v[10:11], v[20:21] op_sel_hi:[1,0]
	v_pk_mul_f32 v[2:3], v[2:3], v[20:21] op_sel_hi:[1,0]
	v_add_f32_e32 v19, 1.0, v19
	v_rcp_f32_e32 v22, v19
	v_mul_f32_e32 v19, 0xbfb8aa3b, v15
	v_exp_f32_e32 v19, v19
	v_pk_mul_f32 v[4:5], v[4:5], v[20:21] op_sel_hi:[1,0]
	s_andn2_b64 vcc, exec, s[0:1]
	v_add_f32_e32 v19, 1.0, v19
	v_rcp_f32_e32 v23, v19
	s_nop 0
	v_pk_mul_f32 v[14:15], v[14:15], v[22:23]
	s_nop 0
	v_pk_mul_f32 v[6:7], v[6:7], v[14:15]
	v_pk_mul_f32 v[14:15], v[16:17], v[20:21] op_sel_hi:[1,0]
	s_nop 0
	v_mul_f32_e32 v16, 0xbfb8aa3b, v14
	v_mul_f32_e32 v17, 0xbfb8aa3b, v15
	v_exp_f32_e32 v16, v16
	v_exp_f32_e32 v17, v17
	v_add_f32_e32 v16, 1.0, v16
	v_add_f32_e32 v17, 1.0, v17
	v_rcp_f32_e32 v16, v16
	v_rcp_f32_e32 v17, v17
	s_nop 0
	v_pk_mul_f32 v[14:15], v[14:15], v[16:17]
	s_nop 0
	v_pk_mul_f32 v[8:9], v[8:9], v[14:15]
	v_mul_f32_e32 v14, 0xbfb8aa3b, v10
	v_mul_f32_e32 v15, 0xbfb8aa3b, v11
	v_exp_f32_e32 v14, v14
	v_exp_f32_e32 v15, v15
	v_add_f32_e32 v14, 1.0, v14
	v_add_f32_e32 v15, 1.0, v15
	v_rcp_f32_e32 v14, v14
	v_rcp_f32_e32 v15, v15
	s_nop 0
	v_pk_mul_f32 v[10:11], v[10:11], v[14:15]
	s_nop 0
	v_pk_mul_f32 v[10:11], v[2:3], v[10:11]
	v_pk_mul_f32 v[2:3], v[12:13], v[20:21] op_sel_hi:[1,0]
	s_nop 0
	v_mul_f32_e32 v12, 0xbfb8aa3b, v2
	v_mul_f32_e32 v13, 0xbfb8aa3b, v3
	v_exp_f32_e32 v12, v12
	v_exp_f32_e32 v13, v13
	v_add_f32_e32 v12, 1.0, v12
	v_add_f32_e32 v13, 1.0, v13
	v_rcp_f32_e32 v12, v12
	v_rcp_f32_e32 v13, v13
	s_nop 0
	v_pk_mul_f32 v[2:3], v[2:3], v[12:13]
	s_nop 0
	v_pk_mul_f32 v[12:13], v[4:5], v[2:3]
	v_cvt_pk_bf16_f32 v2, v6, v7
	v_cvt_pk_bf16_f32 v3, v8, v9
	v_cvt_pk_bf16_f32 v4, v10, v11
	v_cvt_pk_bf16_f32 v5, v12, v13
	v_mad_i64_i32 v[6:7], s[6:7], v18, s4, v[142:143]
	global_store_dwordx4 v[6:7], v[2:5], off
	s_cbranch_vccnz .LBB0_161
	s_andn2_b64 vcc, exec, s[12:13]
	s_cbranch_vccnz .LBB0_160
	s_barrier
	s_branch .LBB0_160

; #define PG8_STAGE(bufoff, gbase, voff) do { _Pragma("unroll") for (int _i = 0; _i < 2; ++_i) \
;         __builtin_amdgcn_global_load_lds((const unsigned*)((const char*)(gbase) + (voff)[_i]), (LAS unsigned*)(lds + (bufoff) + ldsw + _i * 8192), 16, 0, 0); } while (0)
; #define PG8_LDA(dst, b, h) do { _Pragma("unroll") for (int m = 0; m < 4; ++m) _Pragma("unroll") for (int k = 0; k < 2; ++k) dst[m][k] = *(const LAS bf16x8*)(lds + PG8_SA(b, h) + aoff + m * 2048 + k * 1024); } while (0)
; #define PG8_LDB(dst, b, h) do { _Pragma("unroll") for (int n = 0; n < 2; ++n) _Pragma("unroll") for (int k = 0; k < 2; ++k) dst[n][k] = *(const LAS bf16x8*)(lds + PG8_SB(b, h) + boff + n * 2048 + k * 1024); } while (0)
; #define PG8_MMA(ai, bj, At, Bt) do { __builtin_amdgcn_s_setprio(1); _Pragma("unroll") for (int m = 0; m < 4; ++m) _Pragma("unroll") for (int n = 0; n < 2; ++n) _Pragma("unroll") for (int k = 0; k < 2; ++k) \
;         acc[ai][bj][m][n] = __builtin_amdgcn_mfma_f32_16x16x32_bf16(Bt[n][k], At[m][k], acc[ai][bj][m][n], 0, 0, 0); __builtin_amdgcn_s_setprio(0); } while (0)
; #define PG8_WAIT_V(n) asm volatile("s_waitcnt vmcnt(" #n ")" ::: "memory")
; #define PG8_WAIT_L(n) asm volatile("s_waitcnt lgkmcnt(" #n ")" ::: "memory")
; #define PG8_BAR __builtin_amdgcn_s_barrier()
; #define PG8_SCHED __builtin_amdgcn_sched_barrier(0)
; template <class Epi>
; __device__ __forceinline__ void gemm_phase(LAS unsigned char* lds, int wave_s, const Gemm g, const StaticOrder S, const Epi E) {
;     ...
;             PG8_LDB(B0, 0, 0); PG8_LDB(B1, 0, 1); PG8_SCHED; PG8_LDA(At, 0, 0); PG8_STAGE(PG8_SA(1, 1), a1 + hstepA, voffA);
;             PG8_WAIT_V(8); PG8_WAIT_L(0); PG8_BAR; PG8_MMA(0, 0, At, B0); PG8_MMA(0, 1, At, B1); PG8_BAR; PG8_SCHED;
; __global__ void __launch_bounds__(512) fwd_megakernel(Args a) {
;     ...
;             { pg8::Gemm g{HB + r0 * DM, Wb + W_IN, MC, INP, DM, DM}; pg8::StaticOrder S; S.init(MC, INP, G, bx);
;               pg8::EpiGen E{ACT, INP, ssq1 + r0 * 16, 1.f / 1024.f, 1, PQ, PKV, rope, 16, 4}; pg8::gemm_phase(lds, wave_s, g, S, E); }
.LBB0_328:
	s_cmp_eq_u32 s50, 6
	s_cbranch_scc0 .Lsq_win_skip
	v_readlane_b32 s100, v140, 0
	v_readlane_b32 s101, v141, 0
	s_lshl_b32 s6, s4, 14
	s_lshl_b32 s7, s92, 5
	s_add_u32 s6, s6, s7
	s_add_u32 s100, s100, s6
	s_addc_u32 s101, s101, 0
	s_add_i32 m0, s7, 0x24000
	v_lshlrev_b32_e32 v243, 4, v241
	s_nop 1
	global_load_lds_dwordx4 v243, s[100:101]
	global_load_lds_dwordx4 v243, s[100:101] offset:1024

; __device__ __forceinline__ float row_ssq(const float* part, int pitch, int n4, int row, int fq) {
;     f32x4 v = (f32x4){0.f, 0.f, 0.f, 0.f};
;     if (fq < n4) v = *(const f32x4*)(part + (size_t)row * pitch + 4 * fq);
;     float s = (v[0] + v[1]) + (v[2] + v[3]);
;     s += __shfl_xor(s, 16); s += __shfl_xor(s, 32);
;     return s;
; }
;     __device__ __forceinline__ void operator()(const f32x4 (&acc)[2][2][4][2], const Unit& u, int wr, int wc, int fr, int fq) const {
;         const int row0 = u.pm * BM + wr * 64 + fr;
;         float rsv[2][4];
; #pragma unroll
;         for (int ai = 0; ai < 2; ++ai)
; #pragma unroll
;             for (int m = 0; m < 4; ++m) rsv[ai][m] = ssq_in ? rsqrtf(row_ssq(ssq_in, in_pitch, in_n4, row0 + ai * HALF + m * 16, fq) * inv_k + EPS) : 1.f;
.LBB0_331:
	v_readlane_b32 s0, v252, 23
	v_readlane_b32 s1, v252, 24
	v_lshl_add_u32 v156, s4, 8, v139
	v_mov_b32_e32 v163, 1.0
	v_cndmask_b32_e64 v0, 0, 1, s[0:1]
	v_cmp_ne_u32_e64 s[50:51], 1, v0
	s_andn2_b64 vcc, exec, s[0:1]
	v_ashrrev_i32_e32 v157, 31, v156
	v_mov_b32_e32 v164, 1.0
	v_mov_b32_e32 v162, 1.0
	v_mov_b32_e32 v161, 1.0
	v_mov_b32_e32 v160, 1.0
	v_mov_b32_e32 v155, 1.0
	v_mov_b32_e32 v153, 1.0
	v_mov_b32_e32 v151, 1.0
	v_or_b32_e32 v154, 16, v156
	v_or_b32_e32 v152, 32, v156
	v_or_b32_e32 v150, 48, v156
	v_add_u32_e32 v148, 0x80, v156
	v_ashrrev_i32_e32 v149, 31, v148
	s_cbranch_vccnz .Lrsv_win_done
	v_and_b32_e32 v166, 48, v241
	v_lshl_add_u32 v166, v139, 6, v166
	v_add_u32_e32 v166, 0x24000, v166
	ds_read_b128 v[168:171], v166
	ds_read_b128 v[172:175], v166 offset:1024
	ds_read_b128 v[176:179], v166 offset:2048
	ds_read_b128 v[180:183], v166 offset:3072
	v_and_b32_e32 v202, 64, v241
	v_xor_b32_e32 v200, 16, v241
	ds_read_b128 v[184:187], v166 offset:8192
	ds_read_b128 v[188:191], v166 offset:9216
	ds_read_b128 v[192:195], v166 offset:10240
	ds_read_b128 v[196:199], v166 offset:11264
	v_add_u32_e32 v202, 64, v202
	v_cmp_lt_i32_e32 vcc, v200, v202
	v_xor_b32_e32 v201, 32, v241
	s_nop 0
	v_cndmask_b32_e32 v200, v241, v200, vcc
	v_cmp_lt_i32_e32 vcc, v201, v202
	v_lshlrev_b32_e32 v200, 2, v200
	s_nop 0
	v_cndmask_b32_e32 v201, v241, v201, vcc
	v_lshlrev_b32_e32 v201, 2, v201
	s_waitcnt lgkmcnt(7)
	v_add_f32_e32 v168, v168, v169
	v_add_f32_e32 v170, v170, v171
	v_add_f32_e32 v168, v168, v170
	ds_bpermute_b32 v169, v200, v168
	s_waitcnt lgkmcnt(7)
	v_add_f32_e32 v172, v172, v173
	v_add_f32_e32 v174, v174, v175
	v_add_f32_e32 v172, v172, v174
	ds_bpermute_b32 v173, v200, v172
	s_waitcnt lgkmcnt(7)
	v_add_f32_e32 v176, v176, v177
	v_add_f32_e32 v178, v178, v179
	v_add_f32_e32 v176, v176, v178
	ds_bpermute_b32 v177, v200, v176
	s_waitcnt lgkmcnt(7)
	v_add_f32_e32 v180, v180, v181
	v_add_f32_e32 v182, v182, v183
	v_add_f32_e32 v180, v180, v182
	ds_bpermute_b32 v181, v200, v180
	s_waitcnt lgkmcnt(7)
	v_add_f32_e32 v184, v184, v185
	v_add_f32_e32 v186, v186, v187
	v_add_f32_e32 v184, v184, v186
	ds_bpermute_b32 v185, v200, v184
	s_waitcnt lgkmcnt(7)
	v_add_f32_e32 v188, v188, v189
	v_add_f32_e32 v190, v190, v191
	v_add_f32_e32 v188, v188, v190
	ds_bpermute_b32 v189, v200, v188
	s_waitcnt lgkmcnt(7)
	v_add_f32_e32 v192, v192, v193
	v_add_f32_e32 v194, v194, v195
	v_add_f32_e32 v192, v192, v194
	ds_bpermute_b32 v193, v200, v192
	s_waitcnt lgkmcnt(7)
	v_add_f32_e32 v196, v196, v197
	v_add_f32_e32 v198, v198, v199
	v_add_f32_e32 v196, v196, v198
	ds_bpermute_b32 v197, v200, v196
	s_waitcnt lgkmcnt(7)
	v_add_f32_e32 v168, v168, v169
	ds_bpermute_b32 v169, v201, v168
	s_waitcnt lgkmcnt(7)
	v_add_f32_e32 v172, v172, v173
	ds_bpermute_b32 v173, v201, v172
	s_waitcnt lgkmcnt(7)
	v_add_f32_e32 v176, v176, v177
	ds_bpermute_b32 v177, v201, v176
	s_waitcnt lgkmcnt(7)
	v_add_f32_e32 v180, v180, v181
	ds_bpermute_b32 v181, v201, v180
	s_waitcnt lgkmcnt(7)
	v_add_f32_e32 v184, v184, v185
	ds_bpermute_b32 v185, v201, v184
	s_waitcnt lgkmcnt(7)
	v_add_f32_e32 v188, v188, v189
	ds_bpermute_b32 v189, v201, v188
	s_waitcnt lgkmcnt(7)
	v_add_f32_e32 v192, v192, v193
	ds_bpermute_b32 v193, v201, v192
	s_waitcnt lgkmcnt(7)
	v_add_f32_e32 v196, v196, v197
	ds_bpermute_b32 v197, v201, v196
	s_waitcnt lgkmcnt(7)
	v_add_f32_e32 v168, v168, v169
	v_fmamk_f32 v168, v168, 0x3a800000, v239
	s_waitcnt lgkmcnt(6)
	v_add_f32_e32 v172, v172, v173
	v_fmamk_f32 v172, v172, 0x3a800000, v239
	s_waitcnt lgkmcnt(5)
	v_add_f32_e32 v176, v176, v177
	v_fmamk_f32 v176, v176, 0x3a800000, v239
	s_waitcnt lgkmcnt(4)
	v_add_f32_e32 v180, v180, v181
	v_fmamk_f32 v180, v180, 0x3a800000, v239
	s_waitcnt lgkmcnt(3)
	v_add_f32_e32 v184, v184, v185
	v_fmamk_f32 v184, v184, 0x3a800000, v239
	s_waitcnt lgkmcnt(2)
	v_add_f32_e32 v188, v188, v189
	v_fmamk_f32 v188, v188, 0x3a800000, v239
	s_waitcnt lgkmcnt(1)
	v_add_f32_e32 v192, v192, v193
	v_fmamk_f32 v192, v192, 0x3a800000, v239
	s_waitcnt lgkmcnt(0)
	v_add_f32_e32 v196, v196, v197
	v_fmamk_f32 v196, v196, 0x3a800000, v239
	v_cmp_gt_f32_e32 vcc, s55, v168
	v_mul_f32_e32 v169, 0x4b800000, v168
	s_nop 0
	v_cndmask_b32_e32 v168, v168, v169, vcc
	v_rsq_f32_e32 v168, v168
	s_nop 0
	v_mul_f32_e32 v169, 0x45800000, v168
	v_cndmask_b32_e32 v164, v168, v169, vcc
	v_cmp_gt_f32_e32 vcc, s55, v172
	v_mul_f32_e32 v173, 0x4b800000, v172
	s_nop 0
	v_cndmask_b32_e32 v172, v172, v173, vcc
	v_rsq_f32_e32 v172, v172
	s_nop 0
	v_mul_f32_e32 v173, 0x45800000, v172
	v_cndmask_b32_e32 v163, v172, v173, vcc
	v_cmp_gt_f32_e32 vcc, s55, v176
	v_mul_f32_e32 v177, 0x4b800000, v176
	s_nop 0
	v_cndmask_b32_e32 v176, v176, v177, vcc
	v_rsq_f32_e32 v176, v176
	s_nop 0
	v_mul_f32_e32 v177, 0x45800000, v176
	v_cndmask_b32_e32 v162, v176, v177, vcc
	v_cmp_gt_f32_e32 vcc, s55, v180
	v_mul_f32_e32 v181, 0x4b800000, v180
	s_nop 0
	v_cndmask_b32_e32 v180, v180, v181, vcc
	v_rsq_f32_e32 v180, v180
	s_nop 0
	v_mul_f32_e32 v181, 0x45800000, v180
	v_cndmask_b32_e32 v161, v180, v181, vcc
	v_cmp_gt_f32_e32 vcc, s55, v184
	v_mul_f32_e32 v185, 0x4b800000, v184
	s_nop 0
	v_cndmask_b32_e32 v184, v184, v185, vcc
	v_rsq_f32_e32 v184, v184
	s_nop 0
	v_mul_f32_e32 v185, 0x45800000, v184
	v_cndmask_b32_e32 v160, v184, v185, vcc
	v_cmp_gt_f32_e32 vcc, s55, v188
	v_mul_f32_e32 v189, 0x4b800000, v188
	s_nop 0
	v_cndmask_b32_e32 v188, v188, v189, vcc
	v_rsq_f32_e32 v188, v188
	s_nop 0
	v_mul_f32_e32 v189, 0x45800000, v188
	v_cndmask_b32_e32 v155, v188, v189, vcc
	v_cmp_gt_f32_e32 vcc, s55, v192
	v_mul_f32_e32 v193, 0x4b800000, v192
	s_nop 0
	v_cndmask_b32_e32 v192, v192, v193, vcc
	v_rsq_f32_e32 v192, v192
	s_nop 0
	v_mul_f32_e32 v193, 0x45800000, v192
	v_cndmask_b32_e32 v153, v192, v193, vcc
	v_cmp_gt_f32_e32 vcc, s55, v196
	v_mul_f32_e32 v197, 0x4b800000, v196
	s_nop 0
	v_cndmask_b32_e32 v196, v196, v197, vcc
	v_rsq_f32_e32 v196, v196
	s_nop 0
	v_mul_f32_e32 v197, 0x45800000, v196
	v_cndmask_b32_e32 v151, v196, v197, vcc

; #define PG8_STAGE(bufoff, gbase, voff) do { _Pragma("unroll") for (int _i = 0; _i < 2; ++_i) \
;         __builtin_amdgcn_global_load_lds((const unsigned*)((const char*)(gbase) + (voff)[_i]), (LAS unsigned*)(lds + (bufoff) + ldsw + _i * 8192), 16, 0, 0); } while (0)
; #define PG8_LDA(dst, b, h) do { _Pragma("unroll") for (int m = 0; m < 4; ++m) _Pragma("unroll") for (int k = 0; k < 2; ++k) dst[m][k] = *(const LAS bf16x8*)(lds + PG8_SA(b, h) + aoff + m * 2048 + k * 1024); } while (0)
; #define PG8_LDB(dst, b, h) do { _Pragma("unroll") for (int n = 0; n < 2; ++n) _Pragma("unroll") for (int k = 0; k < 2; ++k) dst[n][k] = *(const LAS bf16x8*)(lds + PG8_SB(b, h) + boff + n * 2048 + k * 1024); } while (0)
; #define PG8_MMA(ai, bj, At, Bt) do { __builtin_amdgcn_s_setprio(1); _Pragma("unroll") for (int m = 0; m < 4; ++m) _Pragma("unroll") for (int n = 0; n < 2; ++n) _Pragma("unroll") for (int k = 0; k < 2; ++k) \
;         acc[ai][bj][m][n] = __builtin_amdgcn_mfma_f32_16x16x32_bf16(Bt[n][k], At[m][k], acc[ai][bj][m][n], 0, 0, 0); __builtin_amdgcn_s_setprio(0); } while (0)
; #define PG8_WAIT_V(n) asm volatile("s_waitcnt vmcnt(" #n ")" ::: "memory")
; #define PG8_WAIT_L(n) asm volatile("s_waitcnt lgkmcnt(" #n ")" ::: "memory")
; #define PG8_BAR __builtin_amdgcn_s_barrier()
; #define PG8_SCHED __builtin_amdgcn_sched_barrier(0)
; template <class Epi>
; __device__ __forceinline__ void gemm_phase(LAS unsigned char* lds, int wave_s, const Gemm g, const StaticOrder S, const Epi E) {
;     ...
;             PG8_LDB(B0, 0, 0); PG8_LDB(B1, 0, 1); PG8_SCHED; PG8_LDA(At, 0, 0); PG8_STAGE(PG8_SA(1, 1), a1 + hstepA, voffA);
;             PG8_WAIT_V(8); PG8_WAIT_L(0); PG8_BAR; PG8_MMA(0, 0, At, B0); PG8_MMA(0, 1, At, B1); PG8_BAR; PG8_SCHED;
; __global__ void __launch_bounds__(512) fwd_megakernel(Args a) {
;     ...
;         { pg8::Gemm g{HB, Wb + W_GU2, MTOK, 2 * DFF, DM, DM}; pg8::StaticOrder S; S.init(MTOK, 2 * DFF, G, bx);
;           pg8::EpiSwiglu E{HID, ssq2}; pg8::gemm_phase(lds, wave_s, g, S, E); }
.LBB0_1151:
	s_cmp_eq_u32 s45, 6
	s_cbranch_scc0 .Lsq_ffn2up_skip
	v_readlane_b32 s100, v136, 0
	v_readlane_b32 s101, v137, 0
	s_lshl_b32 s6, s39, 14
	s_lshl_b32 s7, s92, 5
	s_add_u32 s6, s6, s7
	s_add_u32 s100, s100, s6
	s_addc_u32 s101, s101, 0
	s_add_i32 m0, s7, 0x24000
	v_lshlrev_b32_e32 v243, 4, v241
	s_nop 1
	global_load_lds_dwordx4 v243, s[100:101]
	global_load_lds_dwordx4 v243, s[100:101] offset:1024

; __device__ __forceinline__ float row_ssq(const float* part, int pitch, int n4, int row, int fq) {
;     f32x4 v = (f32x4){0.f, 0.f, 0.f, 0.f};
;     if (fq < n4) v = *(const f32x4*)(part + (size_t)row * pitch + 4 * fq);
;     float s = (v[0] + v[1]) + (v[2] + v[3]);
;     s += __shfl_xor(s, 16); s += __shfl_xor(s, 32);
;     return s;
; }
;     __device__ __forceinline__ void operator()(const f32x4 (&acc)[2][2][4][2], const Unit& u, int wr, int wc, int fr, int fq) const {
;         const int row0 = u.pm * BM + wr * 64 + fr, col0 = u.pn * 128 + wc * 32 + 8 * fq;
; #pragma unroll
;         for (int ai = 0; ai < 2; ++ai)
; #pragma unroll
;             for (int m = 0; m < 4; ++m) {
;                 const int row = row0 + ai * HALF + m * 16;
;                 const float rs = rsqrtf(row_ssq(ssq, 16, 4, row, fq) * (1.f / 1024.f) + EPS);
.LBB0_1154:
	v_and_b32_e32 v145, 64, v241
	v_xor_b32_e32 v143, 16, v241
	v_add_u32_e32 v145, 64, v145
	v_cmp_lt_i32_e32 vcc, v143, v145
	v_lshl_add_u32 v144, s39, 8, v146
	v_lshl_or_b32 v142, s4, 7, v148
	v_cndmask_b32_e32 v143, v241, v143, vcc
	v_lshlrev_b32_e32 v150, 2, v143
	v_xor_b32_e32 v143, 32, v241
	v_cmp_lt_i32_e32 vcc, v143, v145
	v_ashrrev_i32_e32 v145, 31, v144
	v_and_b32_e32 v166, 48, v241
	v_lshl_add_u32 v166, v146, 6, v166
	v_add_u32_e32 v166, 0x24000, v166
	ds_read_b128 v[168:171], v166
	ds_read_b128 v[172:175], v166 offset:1024
	ds_read_b128 v[176:179], v166 offset:2048
	ds_read_b128 v[180:183], v166 offset:3072
	v_cndmask_b32_e32 v143, v241, v143, vcc
	v_lshlrev_b32_e32 v151, 2, v143
	ds_read_b128 v[184:187], v166 offset:8192
	ds_read_b128 v[188:191], v166 offset:9216
	ds_read_b128 v[192:195], v166 offset:10240
	ds_read_b128 v[196:199], v166 offset:11264
	v_ashrrev_i32_e32 v143, 31, v142
	v_lshl_add_u64 v[142:143], v[142:143], 1, s[96:97]
	s_movk_i32 s4, 0x1600
	s_mov_b64 s[22:23], -1
	s_waitcnt lgkmcnt(7)
	v_add_f32_e32 v168, v169, v168
	v_add_f32_e32 v170, v170, v171
	v_add_f32_e32 v168, v168, v170
	ds_bpermute_b32 v169, v150, v168
	s_waitcnt lgkmcnt(7)
	v_add_f32_e32 v172, v173, v172
	v_add_f32_e32 v174, v174, v175
	v_add_f32_e32 v172, v172, v174
	ds_bpermute_b32 v173, v150, v172
	s_waitcnt lgkmcnt(7)
	v_add_f32_e32 v176, v177, v176
	v_add_f32_e32 v178, v178, v179
	v_add_f32_e32 v176, v176, v178
	ds_bpermute_b32 v177, v150, v176
	s_waitcnt lgkmcnt(7)
	v_add_f32_e32 v180, v181, v180
	v_add_f32_e32 v182, v182, v183
	v_add_f32_e32 v180, v180, v182
	ds_bpermute_b32 v181, v150, v180
	s_waitcnt lgkmcnt(7)
	v_add_f32_e32 v184, v185, v184
	v_add_f32_e32 v186, v186, v187
	v_add_f32_e32 v184, v184, v186
	ds_bpermute_b32 v185, v150, v184
	s_waitcnt lgkmcnt(7)
	v_add_f32_e32 v188, v189, v188
	v_add_f32_e32 v190, v190, v191
	v_add_f32_e32 v188, v188, v190
	ds_bpermute_b32 v189, v150, v188
	s_waitcnt lgkmcnt(7)
	v_add_f32_e32 v192, v193, v192
	v_add_f32_e32 v194, v194, v195
	v_add_f32_e32 v192, v192, v194
	ds_bpermute_b32 v193, v150, v192
	s_waitcnt lgkmcnt(7)
	v_add_f32_e32 v196, v197, v196
	v_add_f32_e32 v198, v198, v199
	v_add_f32_e32 v196, v196, v198
	ds_bpermute_b32 v197, v150, v196
	s_waitcnt lgkmcnt(7)
	v_add_f32_e32 v168, v168, v169
	ds_bpermute_b32 v169, v151, v168
	s_waitcnt lgkmcnt(7)
	v_add_f32_e32 v172, v172, v173
	ds_bpermute_b32 v173, v151, v172
	s_waitcnt lgkmcnt(7)
	v_add_f32_e32 v176, v176, v177
	ds_bpermute_b32 v177, v151, v176
	s_waitcnt lgkmcnt(7)
	v_add_f32_e32 v180, v180, v181
	ds_bpermute_b32 v181, v151, v180
	s_waitcnt lgkmcnt(7)
	v_add_f32_e32 v184, v184, v185
	ds_bpermute_b32 v185, v151, v184
	s_waitcnt lgkmcnt(7)
	v_add_f32_e32 v188, v188, v189
	ds_bpermute_b32 v189, v151, v188
	s_waitcnt lgkmcnt(7)
	v_add_f32_e32 v192, v192, v193
	ds_bpermute_b32 v193, v151, v192
	s_waitcnt lgkmcnt(7)
	v_add_f32_e32 v196, v196, v197
	ds_bpermute_b32 v197, v151, v196
	s_waitcnt lgkmcnt(7)
	v_add_f32_e32 v168, v168, v169
	v_fmamk_f32 v168, v168, 0x3a800000, v239
	s_waitcnt lgkmcnt(6)
	v_add_f32_e32 v172, v172, v173
	v_fmamk_f32 v172, v172, 0x3a800000, v239
	s_waitcnt lgkmcnt(5)
	v_add_f32_e32 v176, v176, v177
	v_fmamk_f32 v176, v176, 0x3a800000, v239
	s_waitcnt lgkmcnt(4)
	v_add_f32_e32 v180, v180, v181
	v_fmamk_f32 v180, v180, 0x3a800000, v239
	s_waitcnt lgkmcnt(3)
	v_add_f32_e32 v184, v184, v185
	v_fmamk_f32 v184, v184, 0x3a800000, v239
	s_waitcnt lgkmcnt(2)
	v_add_f32_e32 v188, v188, v189
	v_fmamk_f32 v188, v188, 0x3a800000, v239
	s_waitcnt lgkmcnt(1)
	v_add_f32_e32 v192, v192, v193
	v_fmamk_f32 v192, v192, 0x3a800000, v239
	s_waitcnt lgkmcnt(0)
	v_add_f32_e32 v196, v196, v197
	v_fmamk_f32 v196, v196, 0x3a800000, v239
	v_cmp_gt_f32_e32 vcc, s55, v168
	v_mul_f32_e32 v169, 0x4b800000, v168
	s_nop 0
	v_cndmask_b32_e32 v168, v168, v169, vcc
	v_rsq_f32_e32 v168, v168
	s_nop 0
	v_mul_f32_e32 v169, 0x45800000, v168
	v_cndmask_b32_e32 v158, v168, v169, vcc
	v_cmp_gt_f32_e32 vcc, s55, v172
	v_mul_f32_e32 v173, 0x4b800000, v172
	s_nop 0
	v_cndmask_b32_e32 v172, v172, v173, vcc
	v_rsq_f32_e32 v172, v172
	s_nop 0
	v_mul_f32_e32 v173, 0x45800000, v172
	v_cndmask_b32_e32 v159, v172, v173, vcc
	v_cmp_gt_f32_e32 vcc, s55, v176
	v_mul_f32_e32 v177, 0x4b800000, v176
	s_nop 0
	v_cndmask_b32_e32 v176, v176, v177, vcc
	v_rsq_f32_e32 v176, v176
	s_nop 0
	v_mul_f32_e32 v177, 0x45800000, v176
	v_cndmask_b32_e32 v160, v176, v177, vcc
	v_cmp_gt_f32_e32 vcc, s55, v180
	v_mul_f32_e32 v181, 0x4b800000, v180
	s_nop 0
	v_cndmask_b32_e32 v180, v180, v181, vcc
	v_rsq_f32_e32 v180, v180
	s_nop 0
	v_mul_f32_e32 v181, 0x45800000, v180
	v_cndmask_b32_e32 v161, v180, v181, vcc
	v_cmp_gt_f32_e32 vcc, s55, v184
	v_mul_f32_e32 v185, 0x4b800000, v184
	s_nop 0
	v_cndmask_b32_e32 v184, v184, v185, vcc
	v_rsq_f32_e32 v184, v184
	s_nop 0
	v_mul_f32_e32 v185, 0x45800000, v184
	v_cndmask_b32_e32 v162, v184, v185, vcc
	v_cmp_gt_f32_e32 vcc, s55, v188
	v_mul_f32_e32 v189, 0x4b800000, v188
	s_nop 0
	v_cndmask_b32_e32 v188, v188, v189, vcc
	v_rsq_f32_e32 v188, v188
	s_nop 0
	v_mul_f32_e32 v189, 0x45800000, v188
	v_cndmask_b32_e32 v163, v188, v189, vcc
	v_cmp_gt_f32_e32 vcc, s55, v192
	v_mul_f32_e32 v193, 0x4b800000, v192
	s_nop 0
	v_cndmask_b32_e32 v192, v192, v193, vcc
	v_rsq_f32_e32 v192, v192
	s_nop 0
	v_mul_f32_e32 v193, 0x45800000, v192
	v_cndmask_b32_e32 v164, v192, v193, vcc
	v_cmp_gt_f32_e32 vcc, s55, v196
	v_mul_f32_e32 v197, 0x4b800000, v196
	s_nop 0
	v_cndmask_b32_e32 v196, v196, v197, vcc
	v_rsq_f32_e32 v196, v196
	s_nop 0
	v_mul_f32_e32 v197, 0x45800000, v196
	v_cndmask_b32_e32 v165, v196, v197, vcc
	v_mov_b32_e32 v152, v158
; __device__ __forceinline__ unsigned pk2(float lo, float hi) { f32x2_t v = {lo, hi}; bf16x2_t b = __builtin_convertvector(v, bf16x2_t); return __builtin_bit_cast(unsigned, b); }
; __device__ __forceinline__ float fast_sigmoid(float x) { return __builtin_amdgcn_rcpf(1.f + __expf(-x)); }
;     __device__ __forceinline__ void operator()(const f32x4 (&acc)[2][2][4][2], const Unit& u, int wr, int wc, int fr, int fq) const {
;     ...
;                 for (int n = 0; n < 2; ++n)
; #pragma unroll
;                     for (int e = 0; e < 4; ++e) { const float gv = acc[ai][0][m][n][e] * rs, uv = acc[ai][1][m][n][e] * rs; r[n * 4 + e] = gv * fast_sigmoid(gv) * uv; }
;                 u32x4 w; w.x = pk2(r[0], r[1]); w.y = pk2(r[2], r[3]); w.z = pk2(r[4], r[5]); w.w = pk2(r[6], r[7]);
;                 *(u32x4*)(O + (size_t)row * DFF + col0) = w;
	v_pk_mul_f32 v[126:127], v[126:127], v[152:153] op_sel_hi:[1,0]
	v_pk_mul_f32 v[118:119], v[118:119], v[152:153] op_sel_hi:[1,0]
	v_mul_f32_e32 v145, 0xbfb8aa3b, v126
	v_exp_f32_e32 v145, v145
	v_pk_mul_f32 v[120:121], v[120:121], v[152:153] op_sel_hi:[1,0]
	v_pk_mul_f32 v[122:123], v[122:123], v[152:153] op_sel_hi:[1,0]
	v_pk_mul_f32 v[114:115], v[114:115], v[152:153] op_sel_hi:[1,0]
	v_add_f32_e32 v145, 1.0, v145
	v_rcp_f32_e32 v154, v145
	v_mul_f32_e32 v145, 0xbfb8aa3b, v127
	v_exp_f32_e32 v145, v145
	v_pk_mul_f32 v[116:117], v[116:117], v[152:153] op_sel_hi:[1,0]
	v_add_f32_e32 v145, 1.0, v145
	v_rcp_f32_e32 v155, v145
	s_nop 0
	v_pk_mul_f32 v[126:127], v[126:127], v[154:155]
	s_nop 0
	v_pk_mul_f32 v[118:119], v[118:119], v[126:127]
	v_pk_mul_f32 v[126:127], v[128:129], v[152:153] op_sel_hi:[1,0]
	s_nop 0
	v_mul_f32_e32 v128, 0xbfb8aa3b, v126
	v_mul_f32_e32 v129, 0xbfb8aa3b, v127
	v_exp_f32_e32 v128, v128
	v_exp_f32_e32 v129, v129
	v_add_f32_e32 v128, 1.0, v128
	v_add_f32_e32 v129, 1.0, v129
	v_rcp_f32_e32 v128, v128
	v_rcp_f32_e32 v129, v129
	s_nop 0
	v_pk_mul_f32 v[126:127], v[126:127], v[128:129]
	s_nop 0
	v_pk_mul_f32 v[120:121], v[120:121], v[126:127]
	v_mul_f32_e32 v126, 0xbfb8aa3b, v122
	v_mul_f32_e32 v127, 0xbfb8aa3b, v123
	v_exp_f32_e32 v126, v126
	v_exp_f32_e32 v127, v127
	v_add_f32_e32 v126, 1.0, v126
	v_add_f32_e32 v127, 1.0, v127
	v_rcp_f32_e32 v126, v126
	v_rcp_f32_e32 v127, v127
	s_nop 0
	v_pk_mul_f32 v[122:123], v[122:123], v[126:127]
	s_nop 0
	v_pk_mul_f32 v[122:123], v[114:115], v[122:123]
	v_pk_mul_f32 v[114:115], v[124:125], v[152:153] op_sel_hi:[1,0]
	s_nop 0
	v_mul_f32_e32 v124, 0xbfb8aa3b, v114
	v_mul_f32_e32 v125, 0xbfb8aa3b, v115
	v_exp_f32_e32 v124, v124
	v_exp_f32_e32 v125, v125
	v_add_f32_e32 v124, 1.0, v124
	v_add_f32_e32 v125, 1.0, v125
	v_rcp_f32_e32 v124, v124
	v_rcp_f32_e32 v125, v125
	s_nop 0
	v_pk_mul_f32 v[114:115], v[114:115], v[124:125]
	s_nop 0
	v_pk_mul_f32 v[124:125], v[116:117], v[114:115]
	v_cvt_pk_bf16_f32 v114, v118, v119
	v_cvt_pk_bf16_f32 v115, v120, v121
	v_cvt_pk_bf16_f32 v116, v122, v123
	v_cvt_pk_bf16_f32 v117, v124, v125
	v_mad_i64_i32 v[118:119], s[6:7], v144, s4, v[142:143]
	global_store_dwordx4 v[118:119], v[114:117], off
	s_nop 1
	v_or_b32_e32 v114, 16, v144
	v_mov_b32_e32 v116, v159
	v_pk_mul_f32 v[110:111], v[110:111], v[116:117] op_sel_hi:[1,0]
	v_pk_mul_f32 v[102:103], v[102:103], v[116:117] op_sel_hi:[1,0]
	v_mul_f32_e32 v115, 0xbfb8aa3b, v110
	v_exp_f32_e32 v115, v115
	v_pk_mul_f32 v[104:105], v[104:105], v[116:117] op_sel_hi:[1,0]
	v_pk_mul_f32 v[106:107], v[106:107], v[116:117] op_sel_hi:[1,0]
	v_pk_mul_f32 v[98:99], v[98:99], v[116:117] op_sel_hi:[1,0]
	v_add_f32_e32 v115, 1.0, v115
	v_rcp_f32_e32 v118, v115
	v_mul_f32_e32 v115, 0xbfb8aa3b, v111
	v_exp_f32_e32 v115, v115
	v_pk_mul_f32 v[100:101], v[100:101], v[116:117] op_sel_hi:[1,0]
	v_add_f32_e32 v115, 1.0, v115
	v_rcp_f32_e32 v119, v115
	s_nop 0
	v_pk_mul_f32 v[110:111], v[110:111], v[118:119]
	s_nop 0
	v_pk_mul_f32 v[102:103], v[102:103], v[110:111]
	v_pk_mul_f32 v[110:111], v[112:113], v[116:117] op_sel_hi:[1,0]
	s_nop 0
	v_mul_f32_e32 v112, 0xbfb8aa3b, v110
	v_mul_f32_e32 v113, 0xbfb8aa3b, v111
	v_exp_f32_e32 v112, v112
	v_exp_f32_e32 v113, v113
	v_add_f32_e32 v112, 1.0, v112
	v_add_f32_e32 v113, 1.0, v113
	v_rcp_f32_e32 v112, v112
	v_rcp_f32_e32 v113, v113
	s_nop 0
	v_pk_mul_f32 v[110:111], v[110:111], v[112:113]
	s_nop 0
	v_pk_mul_f32 v[104:105], v[104:105], v[110:111]
	v_mul_f32_e32 v110, 0xbfb8aa3b, v106
	v_mul_f32_e32 v111, 0xbfb8aa3b, v107
	v_exp_f32_e32 v110, v110
	v_exp_f32_e32 v111, v111
	v_add_f32_e32 v110, 1.0, v110
	v_add_f32_e32 v111, 1.0, v111
	v_rcp_f32_e32 v110, v110
	v_rcp_f32_e32 v111, v111
	s_nop 0
	v_pk_mul_f32 v[106:107], v[106:107], v[110:111]
	s_nop 0
	v_pk_mul_f32 v[106:107], v[98:99], v[106:107]
	v_pk_mul_f32 v[98:99], v[108:109], v[116:117] op_sel_hi:[1,0]
	s_nop 0
	v_mul_f32_e32 v108, 0xbfb8aa3b, v98
	v_mul_f32_e32 v109, 0xbfb8aa3b, v99
	v_exp_f32_e32 v108, v108
	v_exp_f32_e32 v109, v109
	v_add_f32_e32 v108, 1.0, v108
	v_add_f32_e32 v109, 1.0, v109
	v_rcp_f32_e32 v108, v108
	v_rcp_f32_e32 v109, v109
	s_nop 0
	v_pk_mul_f32 v[98:99], v[98:99], v[108:109]
	s_nop 0
	v_pk_mul_f32 v[108:109], v[100:101], v[98:99]
	v_cvt_pk_bf16_f32 v98, v102, v103
	v_cvt_pk_bf16_f32 v99, v104, v105
	v_cvt_pk_bf16_f32 v100, v106, v107
	v_cvt_pk_bf16_f32 v101, v108, v109
	v_mad_i64_i32 v[102:103], s[6:7], v114, s4, v[142:143]
	global_store_dwordx4 v[102:103], v[98:101], off
	s_nop 1
	v_or_b32_e32 v98, 32, v144
	v_mov_b32_e32 v100, v160
	v_pk_mul_f32 v[94:95], v[94:95], v[100:101] op_sel_hi:[1,0]
	v_pk_mul_f32 v[86:87], v[86:87], v[100:101] op_sel_hi:[1,0]
	v_mul_f32_e32 v99, 0xbfb8aa3b, v94
	v_exp_f32_e32 v99, v99
	v_pk_mul_f32 v[88:89], v[88:89], v[100:101] op_sel_hi:[1,0]
	v_pk_mul_f32 v[90:91], v[90:91], v[100:101] op_sel_hi:[1,0]
	v_pk_mul_f32 v[82:83], v[82:83], v[100:101] op_sel_hi:[1,0]
	v_add_f32_e32 v99, 1.0, v99
	v_rcp_f32_e32 v102, v99
	v_mul_f32_e32 v99, 0xbfb8aa3b, v95
	v_exp_f32_e32 v99, v99
	v_pk_mul_f32 v[84:85], v[84:85], v[100:101] op_sel_hi:[1,0]
	v_add_f32_e32 v99, 1.0, v99
	v_rcp_f32_e32 v103, v99
	s_nop 0
	v_pk_mul_f32 v[94:95], v[94:95], v[102:103]
	s_nop 0
	v_pk_mul_f32 v[86:87], v[86:87], v[94:95]
	v_pk_mul_f32 v[94:95], v[96:97], v[100:101] op_sel_hi:[1,0]
	s_nop 0
	v_mul_f32_e32 v96, 0xbfb8aa3b, v94
	v_mul_f32_e32 v97, 0xbfb8aa3b, v95
	v_exp_f32_e32 v96, v96
	v_exp_f32_e32 v97, v97
	v_add_f32_e32 v96, 1.0, v96
	v_add_f32_e32 v97, 1.0, v97
	v_rcp_f32_e32 v96, v96
	v_rcp_f32_e32 v97, v97
	s_nop 0
	v_pk_mul_f32 v[94:95], v[94:95], v[96:97]
	s_nop 0
	v_pk_mul_f32 v[88:89], v[88:89], v[94:95]
; __device__ __forceinline__ unsigned pk2(float lo, float hi) { f32x2_t v = {lo, hi}; bf16x2_t b = __builtin_convertvector(v, bf16x2_t); return __builtin_bit_cast(unsigned, b); }
; __device__ __forceinline__ float fast_sigmoid(float x) { return __builtin_amdgcn_rcpf(1.f + __expf(-x)); }
;     __device__ __forceinline__ void operator()(const f32x4 (&acc)[2][2][4][2], const Unit& u, int wr, int wc, int fr, int fq) const {
;     ...
;                 for (int n = 0; n < 2; ++n)
; #pragma unroll
;                     for (int e = 0; e < 4; ++e) { const float gv = acc[ai][0][m][n][e] * rs, uv = acc[ai][1][m][n][e] * rs; r[n * 4 + e] = gv * fast_sigmoid(gv) * uv; }
;                 u32x4 w; w.x = pk2(r[0], r[1]); w.y = pk2(r[2], r[3]); w.z = pk2(r[4], r[5]); w.w = pk2(r[6], r[7]);
;                 *(u32x4*)(O + (size_t)row * DFF + col0) = w;
	v_mul_f32_e32 v94, 0xbfb8aa3b, v90
	v_mul_f32_e32 v95, 0xbfb8aa3b, v91
	v_exp_f32_e32 v94, v94
	v_exp_f32_e32 v95, v95
	v_add_f32_e32 v94, 1.0, v94
	v_add_f32_e32 v95, 1.0, v95
	v_rcp_f32_e32 v94, v94
	v_rcp_f32_e32 v95, v95
	s_nop 0
	v_pk_mul_f32 v[90:91], v[90:91], v[94:95]
	s_nop 0
	v_pk_mul_f32 v[90:91], v[82:83], v[90:91]
	v_pk_mul_f32 v[82:83], v[92:93], v[100:101] op_sel_hi:[1,0]
	s_nop 0
	v_mul_f32_e32 v92, 0xbfb8aa3b, v82
	v_mul_f32_e32 v93, 0xbfb8aa3b, v83
	v_exp_f32_e32 v92, v92
	v_exp_f32_e32 v93, v93
	v_add_f32_e32 v92, 1.0, v92
	v_add_f32_e32 v93, 1.0, v93
	v_rcp_f32_e32 v92, v92
	v_rcp_f32_e32 v93, v93
	s_nop 0
	v_pk_mul_f32 v[82:83], v[82:83], v[92:93]
	s_nop 0
	v_pk_mul_f32 v[92:93], v[84:85], v[82:83]
	v_cvt_pk_bf16_f32 v82, v86, v87
	v_cvt_pk_bf16_f32 v83, v88, v89
	v_cvt_pk_bf16_f32 v84, v90, v91
	v_cvt_pk_bf16_f32 v85, v92, v93
	v_mad_i64_i32 v[86:87], s[6:7], v98, s4, v[142:143]
	global_store_dwordx4 v[86:87], v[82:85], off
	s_nop 1
	v_or_b32_e32 v82, 48, v144
	v_mov_b32_e32 v84, v161
	v_pk_mul_f32 v[78:79], v[78:79], v[84:85] op_sel_hi:[1,0]
	v_pk_mul_f32 v[70:71], v[70:71], v[84:85] op_sel_hi:[1,0]
	v_mul_f32_e32 v83, 0xbfb8aa3b, v78
	v_exp_f32_e32 v83, v83
	v_pk_mul_f32 v[72:73], v[72:73], v[84:85] op_sel_hi:[1,0]
	v_pk_mul_f32 v[74:75], v[74:75], v[84:85] op_sel_hi:[1,0]
	v_pk_mul_f32 v[66:67], v[66:67], v[84:85] op_sel_hi:[1,0]
	v_add_f32_e32 v83, 1.0, v83
	v_rcp_f32_e32 v86, v83
	v_mul_f32_e32 v83, 0xbfb8aa3b, v79
	v_exp_f32_e32 v83, v83
	v_pk_mul_f32 v[68:69], v[68:69], v[84:85] op_sel_hi:[1,0]
	v_add_f32_e32 v83, 1.0, v83
	v_rcp_f32_e32 v87, v83
	s_nop 0
	v_pk_mul_f32 v[78:79], v[78:79], v[86:87]
	s_nop 0
	v_pk_mul_f32 v[70:71], v[70:71], v[78:79]
	v_pk_mul_f32 v[78:79], v[80:81], v[84:85] op_sel_hi:[1,0]
	s_nop 0
	v_mul_f32_e32 v80, 0xbfb8aa3b, v78
	v_mul_f32_e32 v81, 0xbfb8aa3b, v79
	v_exp_f32_e32 v80, v80
	v_exp_f32_e32 v81, v81
	v_add_f32_e32 v80, 1.0, v80
	v_add_f32_e32 v81, 1.0, v81
	v_rcp_f32_e32 v80, v80
	v_rcp_f32_e32 v81, v81
	s_nop 0
	v_pk_mul_f32 v[78:79], v[78:79], v[80:81]
	s_nop 0
	v_pk_mul_f32 v[72:73], v[72:73], v[78:79]
	v_mul_f32_e32 v78, 0xbfb8aa3b, v74
	v_mul_f32_e32 v79, 0xbfb8aa3b, v75
	v_exp_f32_e32 v78, v78
	v_exp_f32_e32 v79, v79
	v_add_f32_e32 v78, 1.0, v78
	v_add_f32_e32 v79, 1.0, v79
	v_rcp_f32_e32 v78, v78
	v_rcp_f32_e32 v79, v79
	s_nop 0
	v_pk_mul_f32 v[74:75], v[74:75], v[78:79]
	s_nop 0
	v_pk_mul_f32 v[74:75], v[66:67], v[74:75]
	v_pk_mul_f32 v[66:67], v[76:77], v[84:85] op_sel_hi:[1,0]
	s_nop 0
	v_mul_f32_e32 v76, 0xbfb8aa3b, v66
	v_mul_f32_e32 v77, 0xbfb8aa3b, v67
	v_exp_f32_e32 v76, v76
	v_exp_f32_e32 v77, v77
	v_add_f32_e32 v76, 1.0, v76
	v_add_f32_e32 v77, 1.0, v77
	v_rcp_f32_e32 v76, v76
	v_rcp_f32_e32 v77, v77
	s_nop 0
	v_pk_mul_f32 v[66:67], v[66:67], v[76:77]
	s_nop 0
	v_pk_mul_f32 v[76:77], v[68:69], v[66:67]
	v_cvt_pk_bf16_f32 v66, v70, v71
	v_cvt_pk_bf16_f32 v67, v72, v73
	v_cvt_pk_bf16_f32 v68, v74, v75
	v_cvt_pk_bf16_f32 v69, v76, v77
	v_mad_i64_i32 v[70:71], s[6:7], v82, s4, v[142:143]
	global_store_dwordx4 v[70:71], v[66:69], off
	s_nop 1
	v_add_u32_e32 v66, 0x80, v144
	v_mov_b32_e32 v68, v162
	v_pk_mul_f32 v[62:63], v[62:63], v[68:69] op_sel_hi:[1,0]
	v_pk_mul_f32 v[54:55], v[54:55], v[68:69] op_sel_hi:[1,0]
	v_mul_f32_e32 v67, 0xbfb8aa3b, v62
	v_exp_f32_e32 v67, v67
	v_pk_mul_f32 v[56:57], v[56:57], v[68:69] op_sel_hi:[1,0]
	v_pk_mul_f32 v[58:59], v[58:59], v[68:69] op_sel_hi:[1,0]
	v_pk_mul_f32 v[50:51], v[50:51], v[68:69] op_sel_hi:[1,0]
	v_add_f32_e32 v67, 1.0, v67
	v_rcp_f32_e32 v70, v67
	v_mul_f32_e32 v67, 0xbfb8aa3b, v63
	v_exp_f32_e32 v67, v67
	v_pk_mul_f32 v[52:53], v[52:53], v[68:69] op_sel_hi:[1,0]
	v_add_f32_e32 v67, 1.0, v67
	v_rcp_f32_e32 v71, v67
	s_nop 0
	v_pk_mul_f32 v[62:63], v[62:63], v[70:71]
	s_nop 0
	v_pk_mul_f32 v[54:55], v[54:55], v[62:63]
	v_pk_mul_f32 v[62:63], v[64:65], v[68:69] op_sel_hi:[1,0]
	s_nop 0
	v_mul_f32_e32 v64, 0xbfb8aa3b, v62
	v_mul_f32_e32 v65, 0xbfb8aa3b, v63
	v_exp_f32_e32 v64, v64
	v_exp_f32_e32 v65, v65
	v_add_f32_e32 v64, 1.0, v64
	v_add_f32_e32 v65, 1.0, v65
	v_rcp_f32_e32 v64, v64
	v_rcp_f32_e32 v65, v65
	s_nop 0
	v_pk_mul_f32 v[62:63], v[62:63], v[64:65]
	s_nop 0
	v_pk_mul_f32 v[56:57], v[56:57], v[62:63]
	v_mul_f32_e32 v62, 0xbfb8aa3b, v58
	v_mul_f32_e32 v63, 0xbfb8aa3b, v59
	v_exp_f32_e32 v62, v62
	v_exp_f32_e32 v63, v63
	v_add_f32_e32 v62, 1.0, v62
	v_add_f32_e32 v63, 1.0, v63
	v_rcp_f32_e32 v62, v62
	v_rcp_f32_e32 v63, v63
	s_nop 0
	v_pk_mul_f32 v[58:59], v[58:59], v[62:63]
	s_nop 0
	v_pk_mul_f32 v[58:59], v[50:51], v[58:59]
	v_pk_mul_f32 v[50:51], v[60:61], v[68:69] op_sel_hi:[1,0]
	s_nop 0
	v_mul_f32_e32 v60, 0xbfb8aa3b, v50
	v_mul_f32_e32 v61, 0xbfb8aa3b, v51
	v_exp_f32_e32 v60, v60
	v_exp_f32_e32 v61, v61
	v_add_f32_e32 v60, 1.0, v60
	v_add_f32_e32 v61, 1.0, v61
	v_rcp_f32_e32 v60, v60
	v_rcp_f32_e32 v61, v61
	s_nop 0
	v_pk_mul_f32 v[50:51], v[50:51], v[60:61]
	s_nop 0
	v_pk_mul_f32 v[60:61], v[52:53], v[50:51]
	v_cvt_pk_bf16_f32 v50, v54, v55
	v_cvt_pk_bf16_f32 v51, v56, v57
	v_cvt_pk_bf16_f32 v52, v58, v59
	v_cvt_pk_bf16_f32 v53, v60, v61
	v_mad_i64_i32 v[54:55], s[6:7], v66, s4, v[142:143]
	global_store_dwordx4 v[54:55], v[50:53], off
	s_nop 1
	v_add_u32_e32 v50, 0x90, v144
	v_mov_b32_e32 v52, v163
	v_pk_mul_f32 v[46:47], v[46:47], v[52:53] op_sel_hi:[1,0]
	v_pk_mul_f32 v[38:39], v[38:39], v[52:53] op_sel_hi:[1,0]
	v_mul_f32_e32 v51, 0xbfb8aa3b, v46
	v_exp_f32_e32 v51, v51
	v_pk_mul_f32 v[40:41], v[40:41], v[52:53] op_sel_hi:[1,0]
	v_pk_mul_f32 v[42:43], v[42:43], v[52:53] op_sel_hi:[1,0]
	v_pk_mul_f32 v[34:35], v[34:35], v[52:53] op_sel_hi:[1,0]
	v_add_f32_e32 v51, 1.0, v51
	v_rcp_f32_e32 v54, v51
; template <class Epi>
; __device__ __forceinline__ void gemm_phase(LAS unsigned char* lds, int wave_s, const Gemm g, const StaticOrder S, const Epi E) {
;     ...
;     for (;;) {
;         const bool has_next = S.next(ui + 1, nxt);
;         const char* nA = has_next ? (const char*)g.A + (size_t)nxt.pm * tstepA : cA; const char* nB = has_next ? (const char*)g.Bt + (size_t)nxt.pn * tstepB : cB;
;         for (int t = 0; t < nt; t += 2) {
;             const bool last = (t == nt - 2);
;             const char* a1 = cA + (size_t)(t + 1) * kstep;
;             const char* a2 = last ? nA : cA + (size_t)(t + 2) * kstep; const char* b2 = last ? nB : cB + (size_t)(t + 2) * kstep;
;             const char* a3 = a2 + kstep; const char* b3 = b2 + kstep;
;             PG8_LDB(B0, 0, 0); PG8_LDB(B1, 0, 1); PG8_SCHED; PG8_LDA(At, 0, 0); PG8_STAGE(PG8_SA(1, 1), a1 + hstepA, voffA);
;             PG8_WAIT_V(8); PG8_WAIT_L(0); PG8_BAR; PG8_MMA(0, 0, At, B0); PG8_MMA(0, 1, At, B1); PG8_BAR; PG8_SCHED;
;             PG8_LDA(At, 0, 1); PG8_STAGE(PG8_SB(0, 0), b2, voffB); PG8_STAGE(PG8_SB(0, 1), b2 + hstepB, voffB); PG8_STAGE(PG8_SA(0, 0), a2, voffA);
;             PG8_WAIT_V(8); PG8_WAIT_L(0); PG8_BAR; PG8_MMA(1, 0, At, B0); PG8_MMA(1, 1, At, B1); PG8_BAR; PG8_SCHED;
;             PG8_LDB(B0, 1, 0); PG8_LDB(B1, 1, 1); PG8_SCHED; PG8_LDA(At, 1, 0); PG8_STAGE(PG8_SA(0, 1), a2 + hstepA, voffA);
;             PG8_WAIT_V(8); PG8_WAIT_L(0); PG8_BAR; PG8_MMA(0, 0, At, B0); PG8_MMA(0, 1, At, B1); PG8_BAR; PG8_SCHED;
;             PG8_LDA(At, 1, 1); PG8_STAGE(PG8_SB(1, 0), b3, voffB); PG8_STAGE(PG8_SB(1, 1), b3 + hstepB, voffB); PG8_STAGE(PG8_SA(1, 0), a3, voffA);
;             PG8_WAIT_V(8); PG8_WAIT_L(0); PG8_BAR; PG8_MMA(1, 0, At, B0); PG8_MMA(1, 1, At, B1); PG8_BAR; PG8_SCHED;
;         }
;         if (wr == 0) PG8_BAR;
;     __device__ __forceinline__ void operator()(const f32x4 (&acc)[2][2][4][2], const Unit& u, int wr, int wc, int fr, int fq) const {
;     ...
;                 for (int n = 0; n < 2; ++n)
; #pragma unroll
;                     for (int e = 0; e < 4; ++e) { const float gv = acc[ai][0][m][n][e] * rs, uv = acc[ai][1][m][n][e] * rs; r[n * 4 + e] = gv * fast_sigmoid(gv) * uv; }
;                 u32x4 w; w.x = pk2(r[0], r[1]); w.y = pk2(r[2], r[3]); w.z = pk2(r[4], r[5]); w.w = pk2(r[6], r[7]);
;                 *(u32x4*)(O + (size_t)row * DFF + col0) = w;
	v_mul_f32_e32 v51, 0xbfb8aa3b, v47
	v_exp_f32_e32 v51, v51
	v_pk_mul_f32 v[36:37], v[36:37], v[52:53] op_sel_hi:[1,0]
	v_add_f32_e32 v51, 1.0, v51
	v_rcp_f32_e32 v55, v51
	s_nop 0
	v_pk_mul_f32 v[46:47], v[46:47], v[54:55]
	s_nop 0
	v_pk_mul_f32 v[38:39], v[38:39], v[46:47]
	v_pk_mul_f32 v[46:47], v[48:49], v[52:53] op_sel_hi:[1,0]
	s_nop 0
	v_mul_f32_e32 v48, 0xbfb8aa3b, v46
	v_mul_f32_e32 v49, 0xbfb8aa3b, v47
	v_exp_f32_e32 v48, v48
	v_exp_f32_e32 v49, v49
	v_add_f32_e32 v48, 1.0, v48
	v_add_f32_e32 v49, 1.0, v49
	v_rcp_f32_e32 v48, v48
	v_rcp_f32_e32 v49, v49
	s_nop 0
	v_pk_mul_f32 v[46:47], v[46:47], v[48:49]
	s_nop 0
	v_pk_mul_f32 v[40:41], v[40:41], v[46:47]
	v_mul_f32_e32 v46, 0xbfb8aa3b, v42
	v_mul_f32_e32 v47, 0xbfb8aa3b, v43
	v_exp_f32_e32 v46, v46
	v_exp_f32_e32 v47, v47
	v_add_f32_e32 v46, 1.0, v46
	v_add_f32_e32 v47, 1.0, v47
	v_rcp_f32_e32 v46, v46
	v_rcp_f32_e32 v47, v47
	s_nop 0
	v_pk_mul_f32 v[42:43], v[42:43], v[46:47]
	s_nop 0
	v_pk_mul_f32 v[42:43], v[34:35], v[42:43]
	v_pk_mul_f32 v[34:35], v[44:45], v[52:53] op_sel_hi:[1,0]
	s_nop 0
	v_mul_f32_e32 v44, 0xbfb8aa3b, v34
	v_mul_f32_e32 v45, 0xbfb8aa3b, v35
	v_exp_f32_e32 v44, v44
	v_exp_f32_e32 v45, v45
	v_add_f32_e32 v44, 1.0, v44
	v_add_f32_e32 v45, 1.0, v45
	v_rcp_f32_e32 v44, v44
	v_rcp_f32_e32 v45, v45
	s_nop 0
	v_pk_mul_f32 v[34:35], v[34:35], v[44:45]
	s_nop 0
	v_pk_mul_f32 v[44:45], v[36:37], v[34:35]
	v_cvt_pk_bf16_f32 v34, v38, v39
	v_cvt_pk_bf16_f32 v35, v40, v41
	v_cvt_pk_bf16_f32 v36, v42, v43
	v_cvt_pk_bf16_f32 v37, v44, v45
	v_mad_i64_i32 v[38:39], s[6:7], v50, s4, v[142:143]
	global_store_dwordx4 v[38:39], v[34:37], off
	s_nop 1
	v_add_u32_e32 v34, 0xa0, v144
	v_mov_b32_e32 v36, v164
	v_pk_mul_f32 v[30:31], v[30:31], v[36:37] op_sel_hi:[1,0]
	v_pk_mul_f32 v[22:23], v[22:23], v[36:37] op_sel_hi:[1,0]
	v_mul_f32_e32 v35, 0xbfb8aa3b, v30
	v_exp_f32_e32 v35, v35
	v_pk_mul_f32 v[24:25], v[24:25], v[36:37] op_sel_hi:[1,0]
	v_pk_mul_f32 v[26:27], v[26:27], v[36:37] op_sel_hi:[1,0]
	v_pk_mul_f32 v[18:19], v[18:19], v[36:37] op_sel_hi:[1,0]
	v_add_f32_e32 v35, 1.0, v35
	v_rcp_f32_e32 v38, v35
	v_mul_f32_e32 v35, 0xbfb8aa3b, v31
	v_exp_f32_e32 v35, v35
	v_pk_mul_f32 v[20:21], v[20:21], v[36:37] op_sel_hi:[1,0]
	v_add_f32_e32 v35, 1.0, v35
	v_rcp_f32_e32 v39, v35
	s_nop 0
	v_pk_mul_f32 v[30:31], v[30:31], v[38:39]
	s_nop 0
	v_pk_mul_f32 v[22:23], v[22:23], v[30:31]
	v_pk_mul_f32 v[30:31], v[32:33], v[36:37] op_sel_hi:[1,0]
	s_nop 0
	v_mul_f32_e32 v32, 0xbfb8aa3b, v30
	v_mul_f32_e32 v33, 0xbfb8aa3b, v31
	v_exp_f32_e32 v32, v32
	v_exp_f32_e32 v33, v33
	v_add_f32_e32 v32, 1.0, v32
	v_add_f32_e32 v33, 1.0, v33
	v_rcp_f32_e32 v32, v32
	v_rcp_f32_e32 v33, v33
	s_nop 0
	v_pk_mul_f32 v[30:31], v[30:31], v[32:33]
	s_nop 0
	v_pk_mul_f32 v[24:25], v[24:25], v[30:31]
	v_mul_f32_e32 v30, 0xbfb8aa3b, v26
	v_mul_f32_e32 v31, 0xbfb8aa3b, v27
	v_exp_f32_e32 v30, v30
	v_exp_f32_e32 v31, v31
	v_add_f32_e32 v30, 1.0, v30
	v_add_f32_e32 v31, 1.0, v31
	v_rcp_f32_e32 v30, v30
	v_rcp_f32_e32 v31, v31
	s_nop 0
	v_pk_mul_f32 v[26:27], v[26:27], v[30:31]
	s_nop 0
	v_pk_mul_f32 v[26:27], v[18:19], v[26:27]
	v_pk_mul_f32 v[18:19], v[28:29], v[36:37] op_sel_hi:[1,0]
	s_nop 0
	v_mul_f32_e32 v28, 0xbfb8aa3b, v18
	v_mul_f32_e32 v29, 0xbfb8aa3b, v19
	v_exp_f32_e32 v28, v28
	v_exp_f32_e32 v29, v29
	v_add_f32_e32 v28, 1.0, v28
	v_add_f32_e32 v29, 1.0, v29
	v_rcp_f32_e32 v28, v28
	v_rcp_f32_e32 v29, v29
	s_nop 0
	v_pk_mul_f32 v[18:19], v[18:19], v[28:29]
	s_nop 0
	v_pk_mul_f32 v[28:29], v[20:21], v[18:19]
	v_cvt_pk_bf16_f32 v18, v22, v23
	v_cvt_pk_bf16_f32 v19, v24, v25
	v_cvt_pk_bf16_f32 v20, v26, v27
	v_cvt_pk_bf16_f32 v21, v28, v29
	v_mad_i64_i32 v[22:23], s[6:7], v34, s4, v[142:143]
	global_store_dwordx4 v[22:23], v[18:21], off
	s_nop 1
	v_add_u32_e32 v18, 0xb0, v144
	v_mov_b32_e32 v20, v165
	v_pk_mul_f32 v[14:15], v[14:15], v[20:21] op_sel_hi:[1,0]
	v_pk_mul_f32 v[6:7], v[6:7], v[20:21] op_sel_hi:[1,0]
	v_mul_f32_e32 v19, 0xbfb8aa3b, v14
	v_exp_f32_e32 v19, v19
	v_pk_mul_f32 v[8:9], v[8:9], v[20:21] op_sel_hi:[1,0]
	v_pk_mul_f32 v[10:11], v[10:11], v[20:21] op_sel_hi:[1,0]
	v_pk_mul_f32 v[2:3], v[2:3], v[20:21] op_sel_hi:[1,0]
	v_add_f32_e32 v19, 1.0, v19
	v_rcp_f32_e32 v22, v19
	v_mul_f32_e32 v19, 0xbfb8aa3b, v15
	v_exp_f32_e32 v19, v19
	v_pk_mul_f32 v[4:5], v[4:5], v[20:21] op_sel_hi:[1,0]
	s_andn2_b64 vcc, exec, s[42:43]
	v_add_f32_e32 v19, 1.0, v19
	v_rcp_f32_e32 v23, v19
	s_nop 0
	v_pk_mul_f32 v[14:15], v[14:15], v[22:23]
	s_nop 0
	v_pk_mul_f32 v[6:7], v[6:7], v[14:15]
	v_pk_mul_f32 v[14:15], v[16:17], v[20:21] op_sel_hi:[1,0]
	s_nop 0
	v_mul_f32_e32 v16, 0xbfb8aa3b, v14
	v_mul_f32_e32 v17, 0xbfb8aa3b, v15
	v_exp_f32_e32 v16, v16
	v_exp_f32_e32 v17, v17
	v_add_f32_e32 v16, 1.0, v16
	v_add_f32_e32 v17, 1.0, v17
	v_rcp_f32_e32 v16, v16
	v_rcp_f32_e32 v17, v17
	s_nop 0
	v_pk_mul_f32 v[14:15], v[14:15], v[16:17]
	s_nop 0
	v_pk_mul_f32 v[8:9], v[8:9], v[14:15]
	v_mul_f32_e32 v14, 0xbfb8aa3b, v10
	v_mul_f32_e32 v15, 0xbfb8aa3b, v11
	v_exp_f32_e32 v14, v14
	v_exp_f32_e32 v15, v15
	v_add_f32_e32 v14, 1.0, v14
	v_add_f32_e32 v15, 1.0, v15
	v_rcp_f32_e32 v14, v14
	v_rcp_f32_e32 v15, v15
	s_nop 0
	v_pk_mul_f32 v[10:11], v[10:11], v[14:15]
	s_nop 0
	v_pk_mul_f32 v[10:11], v[2:3], v[10:11]
	v_pk_mul_f32 v[2:3], v[12:13], v[20:21] op_sel_hi:[1,0]
	s_nop 0
	v_mul_f32_e32 v12, 0xbfb8aa3b, v2
	v_mul_f32_e32 v13, 0xbfb8aa3b, v3
	v_exp_f32_e32 v12, v12
	v_exp_f32_e32 v13, v13
	v_add_f32_e32 v12, 1.0, v12
	v_add_f32_e32 v13, 1.0, v13
	v_rcp_f32_e32 v12, v12
	v_rcp_f32_e32 v13, v13
	s_nop 0
	v_pk_mul_f32 v[2:3], v[2:3], v[12:13]
	s_nop 0
	v_pk_mul_f32 v[12:13], v[4:5], v[2:3]
	v_cvt_pk_bf16_f32 v2, v6, v7
	v_cvt_pk_bf16_f32 v3, v8, v9
	v_cvt_pk_bf16_f32 v4, v10, v11
	v_cvt_pk_bf16_f32 v5, v12, v13
	v_mad_i64_i32 v[6:7], s[6:7], v18, s4, v[142:143]
	global_store_dwordx4 v[6:7], v[2:5], off
	s_cbranch_vccnz .LBB0_1147
	s_andn2_b64 vcc, exec, s[0:1]
	s_cbranch_vccnz .LBB0_1146
	s_barrier
	s_branch .LBB0_1146

	.amdhsa_kernel _Z14fwd_megakernel4Args
		.amdhsa_group_segment_fixed_size 16384
		.amdhsa_private_segment_fixed_size 0
		.amdhsa_kernarg_size 496
		.amdhsa_user_sgpr_count 2
		.amdhsa_user_sgpr_dispatch_ptr 0
		.amdhsa_user_sgpr_queue_ptr 0
		.amdhsa_user_sgpr_kernarg_segment_ptr 1
		.amdhsa_user_sgpr_dispatch_id 0
		.amdhsa_user_sgpr_kernarg_preload_length 0
		.amdhsa_user_sgpr_kernarg_preload_offset 0
		.amdhsa_user_sgpr_private_segment_size 0
		.amdhsa_uses_dynamic_stack 0
		.amdhsa_enable_private_segment 0
		.amdhsa_system_sgpr_workgroup_id_x 1
		.amdhsa_system_sgpr_workgroup_id_y 0
		.amdhsa_system_sgpr_workgroup_id_z 0
		.amdhsa_system_sgpr_workgroup_info 0
		.amdhsa_system_vgpr_workitem_id 2
		.amdhsa_next_free_vgpr 256
		.amdhsa_next_free_sgpr 102
		.amdhsa_accum_offset 256
		.amdhsa_reserve_vcc 1
		.amdhsa_float_round_mode_32 0
		.amdhsa_float_round_mode_16_64 0
		.amdhsa_float_denorm_mode_32 3
		.amdhsa_float_denorm_mode_16_64 3
		.amdhsa_dx10_clamp 1
		.amdhsa_ieee_mode 1
		.amdhsa_fp16_overflow 0
		.amdhsa_tg_split 0
		.amdhsa_exception_fp_ieee_invalid_op 0
		.amdhsa_exception_fp_denorm_src 0
		.amdhsa_exception_fp_ieee_div_zero 0
		.amdhsa_exception_fp_ieee_overflow 0
		.amdhsa_exception_fp_ieee_underflow 0
		.amdhsa_exception_fp_ieee_inexact 0
		.amdhsa_exception_int_div_zero 0
	.end_amdhsa_kernel

amdhsa.kernels:
  - .agpr_count:     0
    .args:
      - .offset:         0
        .size:           240
        .value_kind:     by_value
      - .offset:         240
        .size:           4
        .value_kind:     hidden_block_count_x
      - .offset:         244
        .size:           4
        .value_kind:     hidden_block_count_y
      - .offset:         248
        .size:           4
        .value_kind:     hidden_block_count_z
      - .offset:         252
        .size:           2
        .value_kind:     hidden_group_size_x
      - .offset:         254
        .size:           2
        .value_kind:     hidden_group_size_y
      - .offset:         256
        .size:           2
        .value_kind:     hidden_group_size_z
      - .offset:         258
        .size:           2
        .value_kind:     hidden_remainder_x
      - .offset:         260
        .size:           2
        .value_kind:     hidden_remainder_y
      - .offset:         262
        .size:           2
        .value_kind:     hidden_remainder_z
      - .offset:         280
        .size:           8
        .value_kind:     hidden_global_offset_x
      - .offset:         288
        .size:           8
        .value_kind:     hidden_global_offset_y
      - .offset:         296
        .size:           8
        .value_kind:     hidden_global_offset_z
      - .offset:         304
        .size:           2
        .value_kind:     hidden_grid_dims
      - .offset:         328
        .size:           8
        .value_kind:     hidden_multigrid_sync_arg
      - .offset:         360
        .size:           4
        .value_kind:     hidden_dynamic_lds_size
    .group_segment_fixed_size: 16384
    .kernarg_segment_align: 8
    .kernarg_segment_size: 496
    .language:       OpenCL C
    .language_version:
      - 2
      - 0
    .max_flat_workgroup_size: 512
    .name:           _Z14fwd_megakernel4Args
    .private_segment_fixed_size: 0
    .sgpr_count:     108
    .sgpr_spill_count: 376
    .symbol:         _Z14fwd_megakernel4Args.kd
    .uniform_work_group_size: 1
    .uses_dynamic_stack: false
    .vgpr_count:     256
    .vgpr_spill_count: 0
    .wavefront_size: 64
